# packed-f32 (v_pk_mul/v_pk_add) non-transcendental ops in the SwiGLU epilogue + GDN prep item loop no longer drains the previous item's stores at its top, on top of v56
# speedup vs baseline: 1.0231x; 1.0028x over previous
.LBB0_147:
	s_add_u32 s18, s16, 0xfffc0080
	s_addc_u32 s19, s17, -1
	s_add_i32 s83, 0, 0x10000
	v_add_u32_e32 v140, s83, v143
	ds_read_b128 v[146:149], v140
	ds_read_b128 v[150:153], v140 offset:1024
	ds_read_b128 v[154:157], v140 offset:2048
	ds_read_b128 v[158:161], v140 offset:3072
	s_cmp_eq_u32 s82, 12
	s_cselect_b32 s23, s12, s19
	s_cselect_b32 s22, s29, s18
	s_cselect_b32 s19, s9, s79
	s_cselect_b32 s18, s34, s61
	v_lshl_add_u64 v[140:141], s[16:17], 0, v[138:139]
	s_add_i32 m0, s15, 0xc000
	ds_read_b128 v[162:165], v145
	ds_read_b128 v[166:169], v145 offset:1024
	ds_read_b128 v[170:173], v145 offset:2048
	ds_read_b128 v[174:177], v145 offset:3072
	ds_read_b128 v[178:181], v145 offset:4096
	ds_read_b128 v[182:185], v145 offset:5120
	ds_read_b128 v[186:189], v145 offset:6144
	ds_read_b128 v[190:193], v145 offset:7168
	global_load_lds_dwordx4 v[140:141], off
	v_lshl_add_u64 v[140:141], s[16:17], 0, v[136:137]
	s_add_i32 m0, s15, 0xe000
	s_nop 0
	global_load_lds_dwordx4 v[140:141], off
	s_waitcnt lgkmcnt(8)
	s_waitcnt vmcnt(10)
	s_barrier
	s_waitcnt lgkmcnt(0)
	s_waitcnt lgkmcnt(0)
	v_mfma_f32_16x16x32_bf16 v[126:129], v[146:149], v[162:165], v[126:129]
	v_mfma_f32_16x16x32_bf16 v[118:121], v[154:157], v[162:165], v[118:121]
	v_mfma_f32_16x16x32_bf16 v[110:113], v[146:149], v[170:173], v[110:113]
	v_mfma_f32_16x16x32_bf16 v[102:105], v[154:157], v[170:173], v[102:105]
	v_mfma_f32_16x16x32_bf16 v[94:97], v[146:149], v[178:181], v[94:97]
	v_mfma_f32_16x16x32_bf16 v[86:89], v[154:157], v[178:181], v[86:89]
	v_mfma_f32_16x16x32_bf16 v[78:81], v[146:149], v[186:189], v[78:81]
	v_mfma_f32_16x16x32_bf16 v[70:73], v[154:157], v[186:189], v[70:73]
	v_mfma_f32_16x16x32_bf16 v[126:129], v[150:153], v[166:169], v[126:129]
	v_mfma_f32_16x16x32_bf16 v[118:121], v[158:161], v[166:169], v[118:121]
	v_mfma_f32_16x16x32_bf16 v[110:113], v[150:153], v[174:177], v[110:113]
	v_mfma_f32_16x16x32_bf16 v[102:105], v[158:161], v[174:177], v[102:105]
	v_mfma_f32_16x16x32_bf16 v[94:97], v[150:153], v[182:185], v[94:97]
	v_mfma_f32_16x16x32_bf16 v[86:89], v[158:161], v[182:185], v[86:89]
	v_mfma_f32_16x16x32_bf16 v[78:81], v[150:153], v[190:193], v[78:81]
	v_mfma_f32_16x16x32_bf16 v[70:73], v[158:161], v[190:193], v[70:73]
	s_barrier
	s_add_i32 s86, 0, 0x14000
	v_add_u32_e32 v140, s86, v143
	s_add_i32 s83, s83, s51
	ds_read_b128 v[194:197], v140
	ds_read_b128 v[208:211], v140 offset:1024
	ds_read_b128 v[212:215], v140 offset:2048
	ds_read_b128 v[216:219], v140 offset:3072
	v_lshl_add_u64 v[140:141], s[18:19], 0, v[16:17]
	s_mov_b32 m0, s83
	v_lshl_add_u64 v[220:221], s[18:19], 0, v[130:131]
	global_load_lds_dwordx4 v[140:141], off
	s_add_i32 m0, s83, 0x2000
	s_nop 0
	global_load_lds_dwordx4 v[220:221], off
	s_waitcnt vmcnt(10)
	s_barrier
	s_waitcnt lgkmcnt(0)
	s_waitcnt lgkmcnt(0)
	v_mfma_f32_16x16x32_bf16 v[122:125], v[194:197], v[162:165], v[122:125]
	v_mfma_f32_16x16x32_bf16 v[114:117], v[212:215], v[162:165], v[114:117]
	v_mfma_f32_16x16x32_bf16 v[106:109], v[194:197], v[170:173], v[106:109]
	v_mfma_f32_16x16x32_bf16 v[98:101], v[212:215], v[170:173], v[98:101]
	v_mfma_f32_16x16x32_bf16 v[90:93], v[194:197], v[178:181], v[90:93]
	v_mfma_f32_16x16x32_bf16 v[82:85], v[212:215], v[178:181], v[82:85]
	v_mfma_f32_16x16x32_bf16 v[74:77], v[194:197], v[186:189], v[74:77]
	v_mfma_f32_16x16x32_bf16 v[66:69], v[212:215], v[186:189], v[66:69]
	v_mfma_f32_16x16x32_bf16 v[122:125], v[208:211], v[166:169], v[122:125]
	v_mfma_f32_16x16x32_bf16 v[114:117], v[216:219], v[166:169], v[114:117]
	v_mfma_f32_16x16x32_bf16 v[106:109], v[208:211], v[174:177], v[106:109]
	v_mfma_f32_16x16x32_bf16 v[98:101], v[216:219], v[174:177], v[98:101]
	v_mfma_f32_16x16x32_bf16 v[90:93], v[208:211], v[182:185], v[90:93]
	v_mfma_f32_16x16x32_bf16 v[82:85], v[216:219], v[182:185], v[82:85]
	v_mfma_f32_16x16x32_bf16 v[74:77], v[208:211], v[190:193], v[74:77]
	v_mfma_f32_16x16x32_bf16 v[66:69], v[216:219], v[190:193], v[66:69]
	s_mov_b32 m0, s15
	v_lshl_add_u64 v[222:223], s[22:23], 0, v[134:135]
	s_barrier
	ds_read_b128 v[162:165], v145 offset:16384
	ds_read_b128 v[166:169], v145 offset:17408
	ds_read_b128 v[170:173], v145 offset:18432
	ds_read_b128 v[174:177], v145 offset:19456
	ds_read_b128 v[178:181], v145 offset:20480
	ds_read_b128 v[182:185], v145 offset:21504
	ds_read_b128 v[186:189], v145 offset:22528
	ds_read_b128 v[190:193], v145 offset:23552
	global_load_lds_dwordx4 v[222:223], off
	v_lshl_add_u64 v[224:225], s[22:23], 0, v[132:133]
	s_mov_b32 m0, s54
	s_nop 0
	global_load_lds_dwordx4 v[224:225], off
	s_barrier
	s_waitcnt lgkmcnt(0)
	s_waitcnt lgkmcnt(0)
	v_mfma_f32_16x16x32_bf16 v[62:65], v[146:149], v[162:165], v[62:65]
	v_mfma_f32_16x16x32_bf16 v[54:57], v[154:157], v[162:165], v[54:57]
	v_mfma_f32_16x16x32_bf16 v[46:49], v[146:149], v[170:173], v[46:49]
	v_mfma_f32_16x16x32_bf16 v[38:41], v[154:157], v[170:173], v[38:41]
	v_mfma_f32_16x16x32_bf16 v[30:33], v[146:149], v[178:181], v[30:33]
	v_mfma_f32_16x16x32_bf16 v[22:25], v[154:157], v[178:181], v[22:25]
	v_mfma_f32_16x16x32_bf16 v[12:15], v[146:149], v[186:189], v[12:15]
	v_mfma_f32_16x16x32_bf16 v[4:7], v[154:157], v[186:189], v[4:7]
	v_mfma_f32_16x16x32_bf16 v[62:65], v[150:153], v[166:169], v[62:65]
	v_mfma_f32_16x16x32_bf16 v[54:57], v[158:161], v[166:169], v[54:57]
	v_mfma_f32_16x16x32_bf16 v[46:49], v[150:153], v[174:177], v[46:49]
	v_mfma_f32_16x16x32_bf16 v[38:41], v[158:161], v[174:177], v[38:41]
	v_mfma_f32_16x16x32_bf16 v[30:33], v[150:153], v[182:185], v[30:33]
	v_mfma_f32_16x16x32_bf16 v[22:25], v[158:161], v[182:185], v[22:25]
	v_mfma_f32_16x16x32_bf16 v[12:15], v[150:153], v[190:193], v[12:15]
	v_mfma_f32_16x16x32_bf16 v[4:7], v[158:161], v[190:193], v[4:7]
	s_barrier
	s_add_u32 s84, s18, 0x40000
	s_addc_u32 s85, s19, 0
	s_add_i32 s83, s86, s51
	v_lshl_add_u64 v[146:147], s[84:85], 0, v[16:17]
	s_mov_b32 m0, s83
	s_nop 0
	global_load_lds_dwordx4 v[146:147], off
	v_lshl_add_u64 v[146:147], s[84:85], 0, v[130:131]
	s_add_i32 m0, s83, 0x2000
	s_nop 0
	global_load_lds_dwordx4 v[146:147], off
	s_waitcnt vmcnt(10)
	s_barrier
	v_mfma_f32_16x16x32_bf16 v[58:61], v[194:197], v[162:165], v[58:61]
	v_mfma_f32_16x16x32_bf16 v[50:53], v[212:215], v[162:165], v[50:53]
	v_mfma_f32_16x16x32_bf16 v[42:45], v[194:197], v[170:173], v[42:45]
	v_mfma_f32_16x16x32_bf16 v[34:37], v[212:215], v[170:173], v[34:37]
	v_mfma_f32_16x16x32_bf16 v[26:29], v[194:197], v[178:181], v[26:29]
	v_mfma_f32_16x16x32_bf16 v[18:21], v[212:215], v[178:181], v[18:21]
	v_mfma_f32_16x16x32_bf16 v[8:11], v[194:197], v[186:189], v[8:11]
	v_mfma_f32_16x16x32_bf16 v[0:3], v[212:215], v[186:189], v[0:3]
	v_mfma_f32_16x16x32_bf16 v[58:61], v[208:211], v[166:169], v[58:61]
	v_mfma_f32_16x16x32_bf16 v[50:53], v[216:219], v[166:169], v[50:53]
	v_mfma_f32_16x16x32_bf16 v[42:45], v[208:211], v[174:177], v[42:45]
	v_mfma_f32_16x16x32_bf16 v[34:37], v[216:219], v[174:177], v[34:37]
	v_mfma_f32_16x16x32_bf16 v[26:29], v[208:211], v[182:185], v[26:29]
	v_mfma_f32_16x16x32_bf16 v[18:21], v[216:219], v[182:185], v[18:21]
	v_mfma_f32_16x16x32_bf16 v[8:11], v[208:211], v[190:193], v[8:11]
	v_mfma_f32_16x16x32_bf16 v[0:3], v[216:219], v[190:193], v[0:3]
	s_add_i32 s83, 0, 0x18000
	v_add_u32_e32 v158, s83, v143
	s_barrier
	ds_read_b128 v[146:149], v158
	ds_read_b128 v[150:153], v158 offset:1024
	ds_read_b128 v[154:157], v158 offset:2048
	ds_read_b128 v[158:161], v158 offset:3072
	s_add_u32 s22, s22, 0x40000
	s_addc_u32 s23, s23, 0
	s_mov_b32 m0, s55
	v_lshl_add_u64 v[194:195], s[22:23], 0, v[134:135]
	ds_read_b128 v[162:165], v145 offset:32768
	ds_read_b128 v[166:169], v145 offset:33792
	ds_read_b128 v[170:173], v145 offset:34816
	ds_read_b128 v[174:177], v145 offset:35840
	ds_read_b128 v[178:181], v145 offset:36864
	ds_read_b128 v[182:185], v145 offset:37888
	ds_read_b128 v[186:189], v145 offset:38912
	ds_read_b128 v[190:193], v145 offset:39936
	global_load_lds_dwordx4 v[194:195], off
	v_lshl_add_u64 v[194:195], s[22:23], 0, v[132:133]
	s_mov_b32 m0, s56
	s_nop 0
	global_load_lds_dwordx4 v[194:195], off
	s_waitcnt lgkmcnt(8)
	s_waitcnt vmcnt(10)
	s_barrier
	s_waitcnt lgkmcnt(0)
	s_waitcnt lgkmcnt(0)
	v_mfma_f32_16x16x32_bf16 v[126:129], v[146:149], v[162:165], v[126:129]
	v_mfma_f32_16x16x32_bf16 v[118:121], v[154:157], v[162:165], v[118:121]
	v_mfma_f32_16x16x32_bf16 v[110:113], v[146:149], v[170:173], v[110:113]
	v_mfma_f32_16x16x32_bf16 v[102:105], v[154:157], v[170:173], v[102:105]
	v_mfma_f32_16x16x32_bf16 v[94:97], v[146:149], v[178:181], v[94:97]
	v_mfma_f32_16x16x32_bf16 v[86:89], v[154:157], v[178:181], v[86:89]
	v_mfma_f32_16x16x32_bf16 v[78:81], v[146:149], v[186:189], v[78:81]
	v_mfma_f32_16x16x32_bf16 v[70:73], v[154:157], v[186:189], v[70:73]
	v_mfma_f32_16x16x32_bf16 v[126:129], v[150:153], v[166:169], v[126:129]
	v_mfma_f32_16x16x32_bf16 v[118:121], v[158:161], v[166:169], v[118:121]
	v_mfma_f32_16x16x32_bf16 v[110:113], v[150:153], v[174:177], v[110:113]
	v_mfma_f32_16x16x32_bf16 v[102:105], v[158:161], v[174:177], v[102:105]
	v_mfma_f32_16x16x32_bf16 v[94:97], v[150:153], v[182:185], v[94:97]
	v_mfma_f32_16x16x32_bf16 v[86:89], v[158:161], v[182:185], v[86:89]
	v_mfma_f32_16x16x32_bf16 v[78:81], v[150:153], v[190:193], v[78:81]
	v_mfma_f32_16x16x32_bf16 v[70:73], v[158:161], v[190:193], v[70:73]
	s_barrier
	s_add_i32 s22, 0, 0x1c000
	s_add_i32 s23, s83, s51
	v_add_u32_e32 v216, s22, v143
	v_lshl_add_u64 v[140:141], v[140:141], 0, s[10:11]
	s_mov_b32 m0, s23
	ds_read_b128 v[194:197], v216
	ds_read_b128 v[208:211], v216 offset:1024
	ds_read_b128 v[212:215], v216 offset:2048
	ds_read_b128 v[216:219], v216 offset:3072
	global_load_lds_dwordx4 v[140:141], off
	v_lshl_add_u64 v[140:141], v[220:221], 0, s[10:11]
	s_add_i32 m0, s23, 0x2000
	s_nop 0
	global_load_lds_dwordx4 v[140:141], off
	s_waitcnt vmcnt(10)
	s_barrier
	s_waitcnt lgkmcnt(0)
	s_waitcnt lgkmcnt(0)
	v_mfma_f32_16x16x32_bf16 v[122:125], v[194:197], v[162:165], v[122:125]
	v_mfma_f32_16x16x32_bf16 v[114:117], v[212:215], v[162:165], v[114:117]
	v_mfma_f32_16x16x32_bf16 v[106:109], v[194:197], v[170:173], v[106:109]
	v_mfma_f32_16x16x32_bf16 v[98:101], v[212:215], v[170:173], v[98:101]
	v_mfma_f32_16x16x32_bf16 v[90:93], v[194:197], v[178:181], v[90:93]
	v_mfma_f32_16x16x32_bf16 v[82:85], v[212:215], v[178:181], v[82:85]
	v_mfma_f32_16x16x32_bf16 v[74:77], v[194:197], v[186:189], v[74:77]
	v_mfma_f32_16x16x32_bf16 v[66:69], v[212:215], v[186:189], v[66:69]
	v_mfma_f32_16x16x32_bf16 v[122:125], v[208:211], v[166:169], v[122:125]
	v_mfma_f32_16x16x32_bf16 v[114:117], v[216:219], v[166:169], v[114:117]
	v_mfma_f32_16x16x32_bf16 v[106:109], v[208:211], v[174:177], v[106:109]
	v_mfma_f32_16x16x32_bf16 v[98:101], v[216:219], v[174:177], v[98:101]
	v_mfma_f32_16x16x32_bf16 v[90:93], v[208:211], v[182:185], v[90:93]
	v_mfma_f32_16x16x32_bf16 v[82:85], v[216:219], v[182:185], v[82:85]
	v_mfma_f32_16x16x32_bf16 v[74:77], v[208:211], v[190:193], v[74:77]
	v_mfma_f32_16x16x32_bf16 v[66:69], v[216:219], v[190:193], v[66:69]
	s_mov_b32 m0, s57
	v_lshl_add_u64 v[140:141], v[222:223], 0, s[10:11]
	s_barrier
	ds_read_b128 v[162:165], v145 offset:49152
	ds_read_b128 v[166:169], v145 offset:50176
	ds_read_b128 v[170:173], v145 offset:51200
	ds_read_b128 v[174:177], v145 offset:52224
	ds_read_b128 v[178:181], v145 offset:53248
	ds_read_b128 v[182:185], v145 offset:54272
	ds_read_b128 v[186:189], v145 offset:55296
	ds_read_b128 v[190:193], v145 offset:56320
	global_load_lds_dwordx4 v[140:141], off
	v_lshl_add_u64 v[140:141], v[224:225], 0, s[10:11]
	s_mov_b32 m0, s58
	s_nop 0
	global_load_lds_dwordx4 v[140:141], off
	s_barrier
	s_waitcnt lgkmcnt(0)
	s_waitcnt lgkmcnt(0)
	v_mfma_f32_16x16x32_bf16 v[62:65], v[146:149], v[162:165], v[62:65]
	v_mfma_f32_16x16x32_bf16 v[54:57], v[154:157], v[162:165], v[54:57]
	v_mfma_f32_16x16x32_bf16 v[46:49], v[146:149], v[170:173], v[46:49]
	v_mfma_f32_16x16x32_bf16 v[38:41], v[154:157], v[170:173], v[38:41]
	v_mfma_f32_16x16x32_bf16 v[30:33], v[146:149], v[178:181], v[30:33]
	v_mfma_f32_16x16x32_bf16 v[22:25], v[154:157], v[178:181], v[22:25]
	v_mfma_f32_16x16x32_bf16 v[12:15], v[146:149], v[186:189], v[12:15]
	v_mfma_f32_16x16x32_bf16 v[4:7], v[154:157], v[186:189], v[4:7]
	v_mfma_f32_16x16x32_bf16 v[62:65], v[150:153], v[166:169], v[62:65]
	v_mfma_f32_16x16x32_bf16 v[54:57], v[158:161], v[166:169], v[54:57]
	v_mfma_f32_16x16x32_bf16 v[46:49], v[150:153], v[174:177], v[46:49]
	v_mfma_f32_16x16x32_bf16 v[38:41], v[158:161], v[174:177], v[38:41]
	v_mfma_f32_16x16x32_bf16 v[30:33], v[150:153], v[182:185], v[30:33]
	v_mfma_f32_16x16x32_bf16 v[22:25], v[158:161], v[182:185], v[22:25]
	v_mfma_f32_16x16x32_bf16 v[12:15], v[150:153], v[190:193], v[12:15]
	v_mfma_f32_16x16x32_bf16 v[4:7], v[158:161], v[190:193], v[4:7]
	s_barrier
	s_add_u32 s18, s18, 0x40080
	s_addc_u32 s19, s19, 0
	s_add_i32 s22, s22, s51
	v_lshl_add_u64 v[140:141], s[18:19], 0, v[16:17]
	s_mov_b32 m0, s22
	s_nop 0
	global_load_lds_dwordx4 v[140:141], off
	v_lshl_add_u64 v[140:141], s[18:19], 0, v[130:131]
	s_add_i32 m0, s22, 0x2000
	s_nop 0
	global_load_lds_dwordx4 v[140:141], off
	s_waitcnt vmcnt(10)
	s_barrier
	v_mfma_f32_16x16x32_bf16 v[58:61], v[194:197], v[162:165], v[58:61]
	v_mfma_f32_16x16x32_bf16 v[50:53], v[212:215], v[162:165], v[50:53]
	v_mfma_f32_16x16x32_bf16 v[42:45], v[194:197], v[170:173], v[42:45]
	v_mfma_f32_16x16x32_bf16 v[34:37], v[212:215], v[170:173], v[34:37]
	v_mfma_f32_16x16x32_bf16 v[26:29], v[194:197], v[178:181], v[26:29]
	v_mfma_f32_16x16x32_bf16 v[18:21], v[212:215], v[178:181], v[18:21]
	v_mfma_f32_16x16x32_bf16 v[8:11], v[194:197], v[186:189], v[8:11]
	v_mfma_f32_16x16x32_bf16 v[0:3], v[212:215], v[186:189], v[0:3]
	v_mfma_f32_16x16x32_bf16 v[58:61], v[208:211], v[166:169], v[58:61]
	v_mfma_f32_16x16x32_bf16 v[50:53], v[216:219], v[166:169], v[50:53]
	v_mfma_f32_16x16x32_bf16 v[42:45], v[208:211], v[174:177], v[42:45]
	v_mfma_f32_16x16x32_bf16 v[34:37], v[216:219], v[174:177], v[34:37]
	v_mfma_f32_16x16x32_bf16 v[26:29], v[208:211], v[182:185], v[26:29]
	v_mfma_f32_16x16x32_bf16 v[18:21], v[216:219], v[182:185], v[18:21]
	v_mfma_f32_16x16x32_bf16 v[8:11], v[208:211], v[190:193], v[8:11]
	v_mfma_f32_16x16x32_bf16 v[0:3], v[216:219], v[190:193], v[0:3]
	s_add_i32 s82, s82, 2
	s_add_u32 s61, s61, 0x100
	s_addc_u32 s79, s79, 0
	s_add_u32 s16, s16, 0x100
	s_addc_u32 s17, s17, 0
	s_cmp_gt_u32 s82, 13
	s_barrier
	s_cbranch_scc0 .LBB0_147
	s_mov_b32 s100, 0xbfb8aa3b
	s_mov_b32 s101, 0xbfb8aa3b
	v_pk_mul_f32 v[208:209], v[126:127], s[100:101]
	v_pk_mul_f32 v[210:211], v[128:129], s[100:101]
	v_pk_mul_f32 v[212:213], v[118:119], s[100:101]
	v_pk_mul_f32 v[214:215], v[120:121], s[100:101]
	v_exp_f32_e32 v208, v208
	v_exp_f32_e32 v209, v209
	v_exp_f32_e32 v210, v210
	v_exp_f32_e32 v211, v211
	v_exp_f32_e32 v212, v212
	v_exp_f32_e32 v213, v213
	v_exp_f32_e32 v214, v214
	v_exp_f32_e32 v215, v215
	v_pk_add_f32 v[208:209], v[208:209], 1.0 op_sel_hi:[1,0]
	v_pk_add_f32 v[210:211], v[210:211], 1.0 op_sel_hi:[1,0]
	v_pk_add_f32 v[212:213], v[212:213], 1.0 op_sel_hi:[1,0]
	v_pk_add_f32 v[214:215], v[214:215], 1.0 op_sel_hi:[1,0]
	v_rcp_f32_e32 v208, v208
	v_rcp_f32_e32 v209, v209
	v_rcp_f32_e32 v210, v210
	v_rcp_f32_e32 v211, v211
	v_rcp_f32_e32 v212, v212
	v_rcp_f32_e32 v213, v213
	v_rcp_f32_e32 v214, v214
	v_rcp_f32_e32 v215, v215
	v_pk_mul_f32 v[216:217], v[126:127], v[208:209]
	v_pk_mul_f32 v[218:219], v[128:129], v[210:211]
	v_pk_mul_f32 v[220:221], v[118:119], v[212:213]
	v_pk_mul_f32 v[222:223], v[120:121], v[214:215]
	v_pk_mul_f32 v[216:217], v[216:217], v[122:123]
	v_pk_mul_f32 v[218:219], v[218:219], v[124:125]
	v_pk_mul_f32 v[220:221], v[220:221], v[114:115]
	v_pk_mul_f32 v[222:223], v[222:223], v[116:117]
	v_lshl_or_b32 v148, s2, 7, v144
	v_lshl_add_u32 v146, s14, 8, v142
	v_ashrrev_i32_e32 v149, 31, v148
	v_mov_b64_e32 v[140:141], s[94:95]
	v_mad_i64_i32 v[150:151], s[16:17], v146, s65, v[140:141]
	v_lshlrev_b64 v[114:115], 1, v[148:149]
	v_lshl_add_u64 v[120:121], v[150:151], 0, v[114:115]
	v_cvt_pk_bf16_f32 v116, v216, v217
	v_cvt_pk_bf16_f32 v117, v218, v219
	v_cvt_pk_bf16_f32 v118, v220, v221
	v_cvt_pk_bf16_f32 v119, v222, v223
	global_store_dwordx4 v[120:121], v[116:119], off
	v_pk_mul_f32 v[208:209], v[110:111], s[100:101]
	v_pk_mul_f32 v[210:211], v[112:113], s[100:101]
	v_pk_mul_f32 v[212:213], v[102:103], s[100:101]
	v_pk_mul_f32 v[214:215], v[104:105], s[100:101]
	v_exp_f32_e32 v208, v208
	v_exp_f32_e32 v209, v209
	v_exp_f32_e32 v210, v210
	v_exp_f32_e32 v211, v211
	v_exp_f32_e32 v212, v212
	v_exp_f32_e32 v213, v213
	v_exp_f32_e32 v214, v214
	v_exp_f32_e32 v215, v215
	v_pk_add_f32 v[208:209], v[208:209], 1.0 op_sel_hi:[1,0]
	v_pk_add_f32 v[210:211], v[210:211], 1.0 op_sel_hi:[1,0]
	v_pk_add_f32 v[212:213], v[212:213], 1.0 op_sel_hi:[1,0]
	v_pk_add_f32 v[214:215], v[214:215], 1.0 op_sel_hi:[1,0]
	v_rcp_f32_e32 v208, v208
	v_rcp_f32_e32 v209, v209
	v_rcp_f32_e32 v210, v210
	v_rcp_f32_e32 v211, v211
	v_rcp_f32_e32 v212, v212
	v_rcp_f32_e32 v213, v213
	v_rcp_f32_e32 v214, v214
	v_rcp_f32_e32 v215, v215
	v_pk_mul_f32 v[216:217], v[110:111], v[208:209]
	v_pk_mul_f32 v[218:219], v[112:113], v[210:211]
	v_pk_mul_f32 v[220:221], v[102:103], v[212:213]
	v_pk_mul_f32 v[222:223], v[104:105], v[214:215]
	v_pk_mul_f32 v[216:217], v[216:217], v[106:107]
	v_pk_mul_f32 v[218:219], v[218:219], v[108:109]
	v_pk_mul_f32 v[220:221], v[220:221], v[98:99]
	v_pk_mul_f32 v[222:223], v[222:223], v[100:101]
	v_or_b32_e32 v116, 16, v146
	v_mad_i64_i32 v[116:117], s[16:17], v116, s65, v[140:141]
	v_lshl_add_u64 v[102:103], v[116:117], 0, v[114:115]
	v_cvt_pk_bf16_f32 v98, v216, v217
	v_cvt_pk_bf16_f32 v99, v218, v219
	v_cvt_pk_bf16_f32 v100, v220, v221
	v_cvt_pk_bf16_f32 v101, v222, v223
	global_store_dwordx4 v[102:103], v[98:101], off
	v_pk_mul_f32 v[208:209], v[94:95], s[100:101]
	v_pk_mul_f32 v[210:211], v[96:97], s[100:101]
	v_pk_mul_f32 v[212:213], v[86:87], s[100:101]
	v_pk_mul_f32 v[214:215], v[88:89], s[100:101]
	v_exp_f32_e32 v208, v208
	v_exp_f32_e32 v209, v209
	v_exp_f32_e32 v210, v210
	v_exp_f32_e32 v211, v211
	v_exp_f32_e32 v212, v212
	v_exp_f32_e32 v213, v213
	v_exp_f32_e32 v214, v214
	v_exp_f32_e32 v215, v215
	v_pk_add_f32 v[208:209], v[208:209], 1.0 op_sel_hi:[1,0]
	v_pk_add_f32 v[210:211], v[210:211], 1.0 op_sel_hi:[1,0]
	v_pk_add_f32 v[212:213], v[212:213], 1.0 op_sel_hi:[1,0]
	v_pk_add_f32 v[214:215], v[214:215], 1.0 op_sel_hi:[1,0]
	v_rcp_f32_e32 v208, v208
	v_rcp_f32_e32 v209, v209
	v_rcp_f32_e32 v210, v210
	v_rcp_f32_e32 v211, v211
	v_rcp_f32_e32 v212, v212
	v_rcp_f32_e32 v213, v213
	v_rcp_f32_e32 v214, v214
	v_rcp_f32_e32 v215, v215
	v_pk_mul_f32 v[216:217], v[94:95], v[208:209]
	v_pk_mul_f32 v[218:219], v[96:97], v[210:211]
	v_pk_mul_f32 v[220:221], v[86:87], v[212:213]
	v_pk_mul_f32 v[222:223], v[88:89], v[214:215]
	v_pk_mul_f32 v[216:217], v[216:217], v[90:91]
	v_pk_mul_f32 v[218:219], v[218:219], v[92:93]
	v_pk_mul_f32 v[220:221], v[220:221], v[82:83]
	v_pk_mul_f32 v[222:223], v[222:223], v[84:85]
	v_or_b32_e32 v98, 32, v146
	v_mad_i64_i32 v[98:99], s[16:17], v98, s65, v[140:141]
	v_lshl_add_u64 v[86:87], v[98:99], 0, v[114:115]
	v_cvt_pk_bf16_f32 v82, v216, v217
	v_cvt_pk_bf16_f32 v83, v218, v219
	v_cvt_pk_bf16_f32 v84, v220, v221
	v_cvt_pk_bf16_f32 v85, v222, v223
	global_store_dwordx4 v[86:87], v[82:85], off
	v_pk_mul_f32 v[208:209], v[78:79], s[100:101]
	v_pk_mul_f32 v[210:211], v[80:81], s[100:101]
	v_pk_mul_f32 v[212:213], v[70:71], s[100:101]
	v_pk_mul_f32 v[214:215], v[72:73], s[100:101]
	v_exp_f32_e32 v208, v208
	v_exp_f32_e32 v209, v209
	v_exp_f32_e32 v210, v210
	v_exp_f32_e32 v211, v211
	v_exp_f32_e32 v212, v212
	v_exp_f32_e32 v213, v213
	v_exp_f32_e32 v214, v214
	v_exp_f32_e32 v215, v215
	v_pk_add_f32 v[208:209], v[208:209], 1.0 op_sel_hi:[1,0]
	v_pk_add_f32 v[210:211], v[210:211], 1.0 op_sel_hi:[1,0]
	v_pk_add_f32 v[212:213], v[212:213], 1.0 op_sel_hi:[1,0]
	v_pk_add_f32 v[214:215], v[214:215], 1.0 op_sel_hi:[1,0]
	v_rcp_f32_e32 v208, v208
	v_rcp_f32_e32 v209, v209
	v_rcp_f32_e32 v210, v210
	v_rcp_f32_e32 v211, v211
	v_rcp_f32_e32 v212, v212
	v_rcp_f32_e32 v213, v213
	v_rcp_f32_e32 v214, v214
	v_rcp_f32_e32 v215, v215
	v_pk_mul_f32 v[216:217], v[78:79], v[208:209]
	v_pk_mul_f32 v[218:219], v[80:81], v[210:211]
	v_pk_mul_f32 v[220:221], v[70:71], v[212:213]
	v_pk_mul_f32 v[222:223], v[72:73], v[214:215]
	v_pk_mul_f32 v[216:217], v[216:217], v[74:75]
	v_pk_mul_f32 v[218:219], v[218:219], v[76:77]
	v_pk_mul_f32 v[220:221], v[220:221], v[66:67]
	v_pk_mul_f32 v[222:223], v[222:223], v[68:69]
	v_or_b32_e32 v82, 48, v146
	v_mad_i64_i32 v[82:83], s[16:17], v82, s65, v[140:141]
	v_lshl_add_u64 v[70:71], v[82:83], 0, v[114:115]
	v_cvt_pk_bf16_f32 v66, v216, v217
	v_cvt_pk_bf16_f32 v67, v218, v219
	v_cvt_pk_bf16_f32 v68, v220, v221
	v_cvt_pk_bf16_f32 v69, v222, v223
	global_store_dwordx4 v[70:71], v[66:69], off
	v_pk_mul_f32 v[208:209], v[62:63], s[100:101]
	v_pk_mul_f32 v[210:211], v[64:65], s[100:101]
	v_pk_mul_f32 v[212:213], v[54:55], s[100:101]
	v_pk_mul_f32 v[214:215], v[56:57], s[100:101]
	v_exp_f32_e32 v208, v208
	v_exp_f32_e32 v209, v209
	v_exp_f32_e32 v210, v210
	v_exp_f32_e32 v211, v211
	v_exp_f32_e32 v212, v212
	v_exp_f32_e32 v213, v213
	v_exp_f32_e32 v214, v214
	v_exp_f32_e32 v215, v215
	v_pk_add_f32 v[208:209], v[208:209], 1.0 op_sel_hi:[1,0]
	v_pk_add_f32 v[210:211], v[210:211], 1.0 op_sel_hi:[1,0]
	v_pk_add_f32 v[212:213], v[212:213], 1.0 op_sel_hi:[1,0]
	v_pk_add_f32 v[214:215], v[214:215], 1.0 op_sel_hi:[1,0]
	v_rcp_f32_e32 v208, v208
	v_rcp_f32_e32 v209, v209
	v_rcp_f32_e32 v210, v210
	v_rcp_f32_e32 v211, v211
	v_rcp_f32_e32 v212, v212
	v_rcp_f32_e32 v213, v213
	v_rcp_f32_e32 v214, v214
	v_rcp_f32_e32 v215, v215
	v_pk_mul_f32 v[216:217], v[62:63], v[208:209]
	v_pk_mul_f32 v[218:219], v[64:65], v[210:211]
	v_pk_mul_f32 v[220:221], v[54:55], v[212:213]
	v_pk_mul_f32 v[222:223], v[56:57], v[214:215]
	v_pk_mul_f32 v[216:217], v[216:217], v[58:59]
	v_pk_mul_f32 v[218:219], v[218:219], v[60:61]
	v_pk_mul_f32 v[220:221], v[220:221], v[50:51]
	v_pk_mul_f32 v[222:223], v[222:223], v[52:53]
	v_add_u32_e32 v66, 0x80, v146
	v_mad_i64_i32 v[66:67], s[16:17], v66, s65, v[140:141]
	v_lshl_add_u64 v[54:55], v[66:67], 0, v[114:115]
	v_cvt_pk_bf16_f32 v50, v216, v217
	v_cvt_pk_bf16_f32 v51, v218, v219
	v_cvt_pk_bf16_f32 v52, v220, v221
	v_cvt_pk_bf16_f32 v53, v222, v223
	global_store_dwordx4 v[54:55], v[50:53], off
	v_pk_mul_f32 v[208:209], v[46:47], s[100:101]
	v_pk_mul_f32 v[210:211], v[48:49], s[100:101]
	v_pk_mul_f32 v[212:213], v[38:39], s[100:101]
	v_pk_mul_f32 v[214:215], v[40:41], s[100:101]
	v_exp_f32_e32 v208, v208
	v_exp_f32_e32 v209, v209
	v_exp_f32_e32 v210, v210
	v_exp_f32_e32 v211, v211
	v_exp_f32_e32 v212, v212
	v_exp_f32_e32 v213, v213
	v_exp_f32_e32 v214, v214
	v_exp_f32_e32 v215, v215
	v_pk_add_f32 v[208:209], v[208:209], 1.0 op_sel_hi:[1,0]
	v_pk_add_f32 v[210:211], v[210:211], 1.0 op_sel_hi:[1,0]
	v_pk_add_f32 v[212:213], v[212:213], 1.0 op_sel_hi:[1,0]
	v_pk_add_f32 v[214:215], v[214:215], 1.0 op_sel_hi:[1,0]
	v_rcp_f32_e32 v208, v208
	v_rcp_f32_e32 v209, v209
	v_rcp_f32_e32 v210, v210
	v_rcp_f32_e32 v211, v211
	v_rcp_f32_e32 v212, v212
	v_rcp_f32_e32 v213, v213
	v_rcp_f32_e32 v214, v214
	v_rcp_f32_e32 v215, v215
	v_pk_mul_f32 v[216:217], v[46:47], v[208:209]
	v_pk_mul_f32 v[218:219], v[48:49], v[210:211]
	v_pk_mul_f32 v[220:221], v[38:39], v[212:213]
	v_pk_mul_f32 v[222:223], v[40:41], v[214:215]
	v_pk_mul_f32 v[216:217], v[216:217], v[42:43]
	v_pk_mul_f32 v[218:219], v[218:219], v[44:45]
	v_pk_mul_f32 v[220:221], v[220:221], v[34:35]
	v_pk_mul_f32 v[222:223], v[222:223], v[36:37]
	v_add_u32_e32 v50, 0x90, v146
	v_mad_i64_i32 v[50:51], s[16:17], v50, s65, v[140:141]
	v_lshl_add_u64 v[38:39], v[50:51], 0, v[114:115]
	v_cvt_pk_bf16_f32 v34, v216, v217
	v_cvt_pk_bf16_f32 v35, v218, v219
	v_cvt_pk_bf16_f32 v36, v220, v221
	v_cvt_pk_bf16_f32 v37, v222, v223
	global_store_dwordx4 v[38:39], v[34:37], off
	v_pk_mul_f32 v[208:209], v[30:31], s[100:101]
	v_pk_mul_f32 v[210:211], v[32:33], s[100:101]
	v_pk_mul_f32 v[212:213], v[22:23], s[100:101]
	v_pk_mul_f32 v[214:215], v[24:25], s[100:101]
	v_exp_f32_e32 v208, v208
	v_exp_f32_e32 v209, v209
	v_exp_f32_e32 v210, v210
	v_exp_f32_e32 v211, v211
	v_exp_f32_e32 v212, v212
	v_exp_f32_e32 v213, v213
	v_exp_f32_e32 v214, v214
	v_exp_f32_e32 v215, v215
	v_pk_add_f32 v[208:209], v[208:209], 1.0 op_sel_hi:[1,0]
	v_pk_add_f32 v[210:211], v[210:211], 1.0 op_sel_hi:[1,0]
	v_pk_add_f32 v[212:213], v[212:213], 1.0 op_sel_hi:[1,0]
	v_pk_add_f32 v[214:215], v[214:215], 1.0 op_sel_hi:[1,0]
	v_rcp_f32_e32 v208, v208
	v_rcp_f32_e32 v209, v209
	v_rcp_f32_e32 v210, v210
	v_rcp_f32_e32 v211, v211
	v_rcp_f32_e32 v212, v212
	v_rcp_f32_e32 v213, v213
	v_rcp_f32_e32 v214, v214
	v_rcp_f32_e32 v215, v215
	v_pk_mul_f32 v[216:217], v[30:31], v[208:209]
	v_pk_mul_f32 v[218:219], v[32:33], v[210:211]
	v_pk_mul_f32 v[220:221], v[22:23], v[212:213]
	v_pk_mul_f32 v[222:223], v[24:25], v[214:215]
	v_pk_mul_f32 v[216:217], v[216:217], v[26:27]
	v_pk_mul_f32 v[218:219], v[218:219], v[28:29]
	v_pk_mul_f32 v[220:221], v[220:221], v[18:19]
	v_pk_mul_f32 v[222:223], v[222:223], v[20:21]
	v_add_u32_e32 v34, 0xa0, v146
	v_mad_i64_i32 v[34:35], s[16:17], v34, s65, v[140:141]
	v_lshl_add_u64 v[22:23], v[34:35], 0, v[114:115]
	v_cvt_pk_bf16_f32 v18, v216, v217
	v_cvt_pk_bf16_f32 v19, v218, v219
	v_cvt_pk_bf16_f32 v20, v220, v221
	v_cvt_pk_bf16_f32 v21, v222, v223
	global_store_dwordx4 v[22:23], v[18:21], off
	v_pk_mul_f32 v[208:209], v[12:13], s[100:101]
	v_pk_mul_f32 v[210:211], v[14:15], s[100:101]
	v_pk_mul_f32 v[212:213], v[4:5], s[100:101]
	v_pk_mul_f32 v[214:215], v[6:7], s[100:101]
	v_exp_f32_e32 v208, v208
	v_exp_f32_e32 v209, v209
	v_exp_f32_e32 v210, v210
	v_exp_f32_e32 v211, v211
	v_exp_f32_e32 v212, v212
	v_exp_f32_e32 v213, v213
	v_exp_f32_e32 v214, v214
	v_exp_f32_e32 v215, v215
	v_pk_add_f32 v[208:209], v[208:209], 1.0 op_sel_hi:[1,0]
	v_pk_add_f32 v[210:211], v[210:211], 1.0 op_sel_hi:[1,0]
	v_pk_add_f32 v[212:213], v[212:213], 1.0 op_sel_hi:[1,0]
	v_pk_add_f32 v[214:215], v[214:215], 1.0 op_sel_hi:[1,0]
	v_rcp_f32_e32 v208, v208
	v_rcp_f32_e32 v209, v209
	v_rcp_f32_e32 v210, v210
	v_rcp_f32_e32 v211, v211
	v_rcp_f32_e32 v212, v212
	v_rcp_f32_e32 v213, v213
	v_rcp_f32_e32 v214, v214
	v_rcp_f32_e32 v215, v215
	v_pk_mul_f32 v[216:217], v[12:13], v[208:209]
	v_pk_mul_f32 v[218:219], v[14:15], v[210:211]
	v_pk_mul_f32 v[220:221], v[4:5], v[212:213]
	v_pk_mul_f32 v[222:223], v[6:7], v[214:215]
	v_pk_mul_f32 v[216:217], v[216:217], v[8:9]
	v_pk_mul_f32 v[218:219], v[218:219], v[10:11]
	v_pk_mul_f32 v[220:221], v[220:221], v[0:1]
	v_pk_mul_f32 v[222:223], v[222:223], v[2:3]
	v_add_u32_e32 v18, 0xb0, v146
	v_mad_i64_i32 v[18:19], s[16:17], v18, s65, v[140:141]
	v_lshl_add_u64 v[4:5], v[18:19], 0, v[114:115]
	v_cvt_pk_bf16_f32 v0, v216, v217
	v_cvt_pk_bf16_f32 v1, v218, v219
	v_cvt_pk_bf16_f32 v2, v220, v221
	v_cvt_pk_bf16_f32 v3, v222, v223
	global_store_dwordx4 v[4:5], v[0:3], off
	s_and_b64 vcc, exec, s[38:39]
	s_mov_b32 s2, s8
	s_mov_b32 s14, s28
	s_mov_b64 s[16:17], s[42:43]
	s_mov_b64 s[18:19], s[40:41]
	s_cbranch_vccz .LBB0_144
	s_waitcnt vmcnt(0)
	s_cmpk_gt_u32 s48, 0xff
	s_cbranch_scc1 .LBB0_151
	s_barrier

.LBB0_760:
	s_lshr_b32 s2, s13, 2
	s_and_b32 s37, s13, 3
	v_mov_b32_e32 v106, v228
	s_bfe_u32 s8, s13, 0x60002
	s_lshl_b32 s5, s2, 6
	s_lshl_b32 s4, s37, 7
	s_cmp_lg_u32 s8, 0
	v_ashrrev_i32_e32 v104, 3, v106
	s_cselect_b64 s[8:9], -1, 0
	v_cmp_lt_i32_e32 vcc, 2, v104
	v_add_u32_e32 v0, -3, v104
	s_or_b64 vcc, s[8:9], vcc
	v_cndmask_b32_e32 v0, 0, v0, vcc
	v_cndmask_b32_e64 v44, 0, 1.0, vcc
	v_cmp_lt_i32_e32 vcc, 1, v104
	v_add_u32_e32 v4, -2, v104
	s_or_b64 vcc, s[8:9], vcc
	v_cndmask_b32_e32 v4, 0, v4, vcc
	v_cndmask_b32_e64 v42, 0, 1.0, vcc
	v_cmp_lt_i32_e32 vcc, 0, v104
	v_add_u32_e32 v8, -1, v104
	s_or_b64 vcc, s[8:9], vcc
	v_cndmask_b32_e32 v8, 0, v8, vcc
	v_cndmask_b32_e64 v40, 0, 1.0, vcc
	v_cmp_lt_i32_e32 vcc, -1, v104
	s_movk_i32 s2, 0x110
	s_or_b64 vcc, s[8:9], vcc
	v_and_b32_e32 v105, 7, v106
	v_mul_lo_u32 v109, v104, s2
	s_movk_i32 s2, 0x410
	v_cndmask_b32_e32 v14, 0, v104, vcc
	v_lshlrev_b32_e32 v108, 4, v105
	v_mul_lo_u32 v1, v104, s2
	v_add_u32_e32 v0, s5, v0
	v_mov_b64_e32 v[12:13], s[94:95]
	v_add_u32_e32 v4, s5, v4
	v_add_u32_e32 v8, s5, v8
	v_add_u32_e32 v14, s5, v14
	v_add_u32_e32 v107, 0, v1
	v_or_b32_e32 v39, s4, v108
	v_mad_i64_i32 v[0:1], s[38:39], v0, s66, v[12:13]
	v_mad_i64_i32 v[4:5], s[38:39], v4, s66, v[12:13]
	v_mad_i64_i32 v[8:9], s[38:39], v8, s66, v[12:13]
	v_mad_i64_i32 v[12:13], s[8:9], v14, s66, v[12:13]
	v_lshl_add_u64 v[46:47], v[0:1], 0, s[26:27]
	v_lshlrev_b32_e32 v16, 1, v39
	v_lshl_add_u64 v[48:49], v[4:5], 0, s[26:27]
	v_lshl_add_u64 v[50:51], v[8:9], 0, s[26:27]
	v_lshl_add_u64 v[52:53], v[12:13], 0, s[26:27]
	v_lshl_add_u64 v[0:1], v[46:47], 0, v[16:17]
	v_lshl_add_u64 v[4:5], v[48:49], 0, v[16:17]
	v_lshl_add_u64 v[8:9], v[50:51], 0, v[16:17]
	v_lshl_add_u64 v[12:13], v[52:53], 0, v[16:17]
	global_load_dwordx4 v[30:33], v[0:1], off
	s_nop 0
	global_load_dwordx4 v[0:3], v[0:1], off offset:16
	s_nop 0
	global_load_dwordx4 v[26:29], v[4:5], off
	s_nop 0
	global_load_dwordx4 v[4:7], v[4:5], off offset:16
	s_nop 0
	global_load_dwordx4 v[22:25], v[8:9], off
	s_nop 0
	global_load_dwordx4 v[8:11], v[8:9], off offset:16
	s_nop 0
	global_load_dwordx4 v[18:21], v[12:13], off
	s_nop 0
	global_load_dwordx4 v[12:15], v[12:13], off offset:16
	s_mov_b32 s8, 0
	s_ashr_i32 s9, s8, 31
	s_lshl_b64 s[8:9], s[8:9], 3
	s_add_u32 s8, s0, s8
	s_addc_u32 s9, s1, s9
	s_load_dwordx2 s[98:99], s[0:1], 0x98
	s_load_dwordx2 s[100:101], s[0:1], 0xa0
	s_load_dwordx2 s[8:9], s[8:9], 0x90
	v_lshlrev_b32_e32 v41, 2, v39
	v_cndmask_b32_e64 v38, 0, 1.0, vcc
	v_and_b32_e32 v111, 64, v234
	v_or_b32_e32 v16, 0x400, v16
	s_waitcnt lgkmcnt(0)
	v_or_b32_e32 v188, s5, v228
	v_lshlrev_b32_e32 v188, 5, v188
	v_lshl_add_u32 v188, s37, 2, v188
	global_load_dword v189, v188, s[42:43] offset:16
	global_load_dword v190, v188, s[42:43]
	v_mov_b32_e32 v188, s37
	v_or_b32_e32 v188, s35, v188
	v_lshlrev_b32_e32 v188, 2, v188
	global_load_dword v191, v188, s[98:99]
	global_load_dword v192, v188, s[100:101]
	s_add_u32 s98, s8, s16
	s_addc_u32 s99, s9, s17
	s_add_u32 s100, s8, s18
	s_addc_u32 s101, s9, s19
	s_add_u32 s30, s8, s22
	s_addc_u32 s31, s9, s23
	s_add_u32 s8, s8, s15
	s_addc_u32 s9, s9, s14
	global_load_dwordx4 v[34:37], v41, s[8:9] offset:48
	global_load_dwordx4 v[54:57], v41, s[8:9] offset:32
	global_load_dwordx4 v[58:61], v41, s[8:9] offset:16
	global_load_dwordx4 v[62:65], v41, s[8:9]
	global_load_dwordx4 v[140:143], v41, s[98:99] offset:48
	global_load_dwordx4 v[144:147], v41, s[98:99] offset:32
	global_load_dwordx4 v[148:151], v41, s[98:99] offset:16
	global_load_dwordx4 v[152:155], v41, s[98:99]
	global_load_dwordx4 v[156:159], v41, s[100:101] offset:48
	global_load_dwordx4 v[160:163], v41, s[100:101] offset:32
	global_load_dwordx4 v[164:167], v41, s[100:101] offset:16
	global_load_dwordx4 v[168:171], v41, s[100:101]
	global_load_dwordx4 v[172:175], v41, s[30:31] offset:48
	global_load_dwordx4 v[176:179], v41, s[30:31] offset:32
	global_load_dwordx4 v[180:183], v41, s[30:31] offset:16
	global_load_dwordx4 v[184:187], v41, s[30:31]
	v_lshl_add_u64 v[138:139], v[46:47], 0, v[16:17]
	v_lshl_add_u64 v[194:195], v[48:49], 0, v[16:17]
	v_lshl_add_u64 v[196:197], v[50:51], 0, v[16:17]
	v_lshl_add_u64 v[252:253], v[52:53], 0, v[16:17]
	global_load_dwordx4 v[208:211], v[138:139], off
	global_load_dwordx4 v[212:215], v[138:139], off offset:16
	global_load_dwordx4 v[216:219], v[194:195], off
	global_load_dwordx4 v[220:223], v[194:195], off offset:16
	global_load_dwordx4 v[224:227], v[196:197], off
	global_load_dwordx4 v[240:243], v[196:197], off offset:16
	global_load_dwordx4 v[244:247], v[252:253], off
	global_load_dwordx4 v[248:251], v[252:253], off offset:16
	s_mov_b32 s8, 0
	s_ashr_i32 s9, s8, 31
	s_lshl_b64 s[8:9], s[8:9], 3
	s_add_u32 s8, s0, s8
	s_addc_u32 s9, s1, s9
	v_lshl_add_u32 v110, v105, 6, v107
	s_waitcnt lgkmcnt(0)
	s_add_u32 s8, s8, s16
	s_addc_u32 s9, s9, s17
	s_waitcnt vmcnt(8)
	v_lshlrev_b32_e32 v43, 16, v30
	v_and_b32_e32 v30, 0xffff0000, v30
	v_lshlrev_b32_e32 v84, 16, v18
	v_and_b32_e32 v18, 0xffff0000, v18
	v_pk_mul_f32 v[58:59], v[44:45], v[58:59] op_sel_hi:[0,1]
	v_pk_mul_f32 v[62:63], v[44:45], v[62:63] op_sel_hi:[0,1]
	v_pk_mul_f32 v[64:65], v[44:45], v[64:65] op_sel_hi:[0,1]
	v_fma_f32 v82, v63, v30, 0
	v_lshlrev_b32_e32 v30, 16, v31
	v_fma_f32 v83, v62, v43, 0
	v_fma_f32 v81, v64, v30, 0
	v_and_b32_e32 v30, 0xffff0000, v31
	v_lshlrev_b32_e32 v43, 16, v32
	v_and_b32_e32 v32, 0xffff0000, v32
	v_fma_f32 v80, v65, v30, 0
	v_pk_mul_f32 v[30:31], v[44:45], v[60:61] op_sel_hi:[0,1]
	v_fma_f32 v78, v59, v32, 0
	v_lshlrev_b32_e32 v32, 16, v33
	v_fma_f32 v45, v30, v32, 0
	v_and_b32_e32 v30, 0xffff0000, v33
	v_fma_f32 v79, v58, v43, 0
	v_fma_f32 v43, v31, v30, 0
	v_pk_mul_f32 v[58:59], v[44:45], v[56:57] op_sel_hi:[0,1]
	v_pk_mul_f32 v[62:63], v[44:45], v[54:55] op_sel_hi:[0,1]
	v_pk_mul_f32 v[54:55], v[44:45], v[36:37] op_sel_hi:[0,1]
	v_pk_mul_f32 v[56:57], v[44:45], v[34:35] op_sel_hi:[0,1]
	v_mov_b64_e32 v[30:31], v[140:141]
	v_mov_b64_e32 v[32:33], v[142:143]
	v_mov_b64_e32 v[34:35], v[144:145]
	v_mov_b64_e32 v[36:37], v[146:147]
	v_mov_b64_e32 v[64:65], v[148:149]
	v_mov_b64_e32 v[66:67], v[150:151]
	v_mov_b64_e32 v[68:69], v[152:153]
	v_mov_b64_e32 v[70:71], v[154:155]
	s_mov_b32 s8, 0
	s_ashr_i32 s9, s8, 31
	s_lshl_b64 s[8:9], s[8:9], 3
	s_add_u32 s8, s0, s8
	s_addc_u32 s9, s1, s9
	s_waitcnt lgkmcnt(0)
	s_add_u32 s8, s8, s18
	s_addc_u32 s9, s9, s19
	s_waitcnt vmcnt(8)
	v_pk_mul_f32 v[60:61], v[42:43], v[70:71] op_sel_hi:[0,1]
	v_pk_mul_f32 v[68:69], v[42:43], v[68:69] op_sel_hi:[0,1]
	v_lshlrev_b32_e32 v70, 16, v26
	v_and_b32_e32 v26, 0xffff0000, v26
	v_fmac_f32_e32 v82, v69, v26
	v_lshlrev_b32_e32 v26, 16, v27
	v_fmac_f32_e32 v81, v60, v26
	v_and_b32_e32 v26, 0xffff0000, v27
	v_fmac_f32_e32 v80, v61, v26
	v_pk_mul_f32 v[60:61], v[42:43], v[64:65] op_sel_hi:[0,1]
	v_lshlrev_b32_e32 v64, 16, v28
	v_and_b32_e32 v28, 0xffff0000, v28
	v_pk_mul_f32 v[26:27], v[42:43], v[66:67] op_sel_hi:[0,1]
	v_fmac_f32_e32 v78, v61, v28
	v_lshlrev_b32_e32 v28, 16, v29
	v_fmac_f32_e32 v45, v26, v28
	v_and_b32_e32 v26, 0xffff0000, v29
	v_fmac_f32_e32 v43, v27, v26
	v_fmac_f32_e32 v83, v68, v70
	v_fmac_f32_e32 v79, v60, v64
	v_pk_mul_f32 v[66:67], v[42:43], v[36:37] op_sel_hi:[0,1]
	v_pk_mul_f32 v[70:71], v[42:43], v[34:35] op_sel_hi:[0,1]
	v_pk_mul_f32 v[60:61], v[42:43], v[32:33] op_sel_hi:[0,1]
	v_pk_mul_f32 v[64:65], v[42:43], v[30:31] op_sel_hi:[0,1]
	v_mov_b64_e32 v[26:27], v[156:157]
	v_mov_b64_e32 v[28:29], v[158:159]
	v_mov_b64_e32 v[30:31], v[160:161]
	v_mov_b64_e32 v[32:33], v[162:163]
	v_mov_b64_e32 v[34:35], v[164:165]
	v_mov_b64_e32 v[36:37], v[166:167]
	v_mov_b64_e32 v[72:73], v[168:169]
	v_mov_b64_e32 v[74:75], v[170:171]
	s_mov_b32 s8, 0
	s_ashr_i32 s9, s8, 31
	s_lshl_b64 s[8:9], s[8:9], 3
	s_add_u32 s8, s0, s8
	s_addc_u32 s9, s1, s9
	s_waitcnt lgkmcnt(0)
	s_add_u32 s8, s8, s22
	s_addc_u32 s9, s9, s23
	s_waitcnt vmcnt(10)
	v_pk_mul_f32 v[76:77], v[40:41], v[30:31] op_sel_hi:[0,1]
	s_waitcnt vmcnt(9)
	v_pk_mul_f32 v[34:35], v[40:41], v[34:35] op_sel_hi:[0,1]
	s_waitcnt vmcnt(8)
	v_pk_mul_f32 v[68:69], v[40:41], v[74:75] op_sel_hi:[0,1]
	v_pk_mul_f32 v[72:73], v[40:41], v[72:73] op_sel_hi:[0,1]
	v_lshlrev_b32_e32 v74, 16, v22
	v_and_b32_e32 v22, 0xffff0000, v22
	v_fmac_f32_e32 v82, v73, v22
	v_lshlrev_b32_e32 v22, 16, v23
	v_fmac_f32_e32 v81, v68, v22
	v_and_b32_e32 v22, 0xffff0000, v23
	v_fmac_f32_e32 v80, v69, v22
	v_pk_mul_f32 v[22:23], v[40:41], v[36:37] op_sel_hi:[0,1]
	v_lshlrev_b32_e32 v36, 16, v24
	v_and_b32_e32 v24, 0xffff0000, v24
	v_fmac_f32_e32 v78, v35, v24
	v_lshlrev_b32_e32 v24, 16, v25
	v_fmac_f32_e32 v45, v22, v24
	v_and_b32_e32 v22, 0xffff0000, v25
	v_fmac_f32_e32 v83, v72, v74
	v_fmac_f32_e32 v79, v34, v36
	v_fmac_f32_e32 v43, v23, v22
	v_pk_mul_f32 v[74:75], v[40:41], v[32:33] op_sel_hi:[0,1]
	v_pk_mul_f32 v[68:69], v[40:41], v[28:29] op_sel_hi:[0,1]
	v_pk_mul_f32 v[72:73], v[40:41], v[26:27] op_sel_hi:[0,1]
	v_mov_b64_e32 v[22:23], v[172:173]
	v_mov_b64_e32 v[24:25], v[174:175]
	v_mov_b64_e32 v[26:27], v[176:177]
	v_mov_b64_e32 v[28:29], v[178:179]
	v_mov_b64_e32 v[30:31], v[180:181]
	v_mov_b64_e32 v[32:33], v[182:183]
	v_mov_b64_e32 v[34:35], v[184:185]
	v_mov_b64_e32 v[36:37], v[186:187]
	s_waitcnt vmcnt(10)
	v_pk_mul_f32 v[26:27], v[38:39], v[26:27] op_sel_hi:[0,1]
	s_waitcnt vmcnt(9)
	v_pk_mul_f32 v[30:31], v[38:39], v[30:31] op_sel_hi:[0,1]
	s_waitcnt vmcnt(8)
	v_pk_mul_f32 v[34:35], v[38:39], v[34:35] op_sel_hi:[0,1]
	v_pk_mul_f32 v[36:37], v[38:39], v[36:37] op_sel_hi:[0,1]
	v_fmac_f32_e32 v82, v35, v18
	v_lshlrev_b32_e32 v18, 16, v19
	v_fmac_f32_e32 v81, v36, v18
	v_and_b32_e32 v18, 0xffff0000, v19
	v_fmac_f32_e32 v80, v37, v18
	v_pk_mul_f32 v[18:19], v[38:39], v[32:33] op_sel_hi:[0,1]
	v_lshlrev_b32_e32 v32, 16, v20
	v_and_b32_e32 v20, 0xffff0000, v20
	v_fmac_f32_e32 v83, v34, v84
	v_fmac_f32_e32 v78, v31, v20
	v_lshlrev_b32_e32 v20, 16, v21
	v_fmac_f32_e32 v45, v18, v20
	v_and_b32_e32 v18, 0xffff0000, v21
	v_pk_mul_f32 v[20:21], v[38:39], v[22:23] op_sel_hi:[0,1]
	v_mul_f32_e32 v22, 0xbfb8aa3b, v83
	v_exp_f32_e32 v22, v22
	v_fmac_f32_e32 v79, v30, v32
	v_fmac_f32_e32 v43, v19, v18
	v_and_b32_e32 v23, 0xffff0000, v0
	v_add_f32_e32 v22, 1.0, v22
	v_rcp_f32_e32 v22, v22
	v_pk_mul_f32 v[18:19], v[38:39], v[24:25] op_sel_hi:[0,1]
	v_and_b32_e32 v25, 0xffff0000, v4
	v_lshlrev_b32_e32 v24, 16, v4
	v_mul_f32_e32 v30, v83, v22
	v_mul_f32_e32 v22, 0xbfb8aa3b, v82
	v_exp_f32_e32 v22, v22
	v_lshlrev_b32_e32 v4, 16, v9
	v_pk_mul_f32 v[28:29], v[38:39], v[28:29] op_sel_hi:[0,1]
	v_add_f32_e32 v22, 1.0, v22
	v_rcp_f32_e32 v22, v22
	s_nop 0
	v_mul_f32_e32 v31, v82, v22
	v_mul_f32_e32 v22, 0xbfb8aa3b, v81
	v_exp_f32_e32 v22, v22
	s_nop 0
	v_add_f32_e32 v22, 1.0, v22
	v_rcp_f32_e32 v22, v22
	s_nop 0
	v_mul_f32_e32 v32, v81, v22
	v_mul_f32_e32 v22, 0xbfb8aa3b, v80
	v_exp_f32_e32 v22, v22
	s_nop 0
	v_add_f32_e32 v22, 1.0, v22
	v_rcp_f32_e32 v22, v22
	s_nop 0
	v_mul_f32_e32 v33, v80, v22
	v_mul_f32_e32 v22, 0xbfb8aa3b, v79
	v_exp_f32_e32 v22, v22
	s_nop 0
	v_add_f32_e32 v22, 1.0, v22
	v_rcp_f32_e32 v22, v22
	s_nop 0
	v_mul_f32_e32 v34, v79, v22
	v_mul_f32_e32 v22, 0xbfb8aa3b, v78
	v_exp_f32_e32 v22, v22
	s_nop 0
	v_add_f32_e32 v22, 1.0, v22
	v_rcp_f32_e32 v22, v22
	s_nop 0
	v_mul_f32_e32 v35, v78, v22
	v_mul_f32_e32 v22, 0xbfb8aa3b, v45
	v_exp_f32_e32 v22, v22
	s_nop 0
	v_add_f32_e32 v22, 1.0, v22
	v_rcp_f32_e32 v22, v22
	s_nop 0
	v_mul_f32_e32 v36, v45, v22
	v_mul_f32_e32 v22, 0xbfb8aa3b, v43
	v_exp_f32_e32 v22, v22
	s_nop 0
	v_add_f32_e32 v22, 1.0, v22
	v_rcp_f32_e32 v22, v22
	s_nop 0
	v_mul_f32_e32 v37, v43, v22
	v_lshlrev_b32_e32 v22, 16, v0
	v_pk_fma_f32 v[22:23], v[62:63], v[22:23], 0 op_sel_hi:[1,1,0]
	v_mul_f32_e32 v43, v31, v31
	v_pk_fma_f32 v[22:23], v[70:71], v[24:25], v[22:23]
	v_and_b32_e32 v25, 0xffff0000, v8
	v_lshlrev_b32_e32 v24, 16, v8
	v_pk_fma_f32 v[22:23], v[76:77], v[24:25], v[22:23]
	v_and_b32_e32 v25, 0xffff0000, v12
	v_lshlrev_b32_e32 v24, 16, v12
	v_pk_fma_f32 v[22:23], v[26:27], v[24:25], v[22:23]
	v_fmac_f32_e32 v43, v30, v30
	v_mul_f32_e32 v0, 0xbfb8aa3b, v22
	v_exp_f32_e32 v0, v0
	v_fmac_f32_e32 v43, v32, v32
	v_fmac_f32_e32 v43, v33, v33
	v_fmac_f32_e32 v43, v34, v34
	v_add_f32_e32 v0, 1.0, v0
	v_rcp_f32_e32 v24, v0
	v_mul_f32_e32 v0, 0xbfb8aa3b, v23
	v_exp_f32_e32 v0, v0
	v_fmac_f32_e32 v43, v35, v35
	v_fmac_f32_e32 v43, v36, v36
	v_fmac_f32_e32 v43, v37, v37
	v_add_f32_e32 v0, 1.0, v0
	v_rcp_f32_e32 v25, v0
	s_nop 0
	v_pk_mul_f32 v[22:23], v[22:23], v[24:25]
	s_nop 0
	v_pk_mul_f32 v[24:25], v[22:23], v[22:23]
	s_nop 0
	v_add_f32_e32 v0, v24, v43
	v_add_f32_e32 v8, v25, v0
	v_and_b32_e32 v25, 0xffff0000, v1
	v_lshlrev_b32_e32 v24, 16, v1
	v_pk_fma_f32 v[0:1], v[58:59], v[24:25], 0 op_sel_hi:[1,1,0]
	v_and_b32_e32 v25, 0xffff0000, v5
	v_lshlrev_b32_e32 v24, 16, v5
	v_pk_fma_f32 v[0:1], v[66:67], v[24:25], v[0:1]
	v_and_b32_e32 v5, 0xffff0000, v9
	v_pk_fma_f32 v[0:1], v[74:75], v[4:5], v[0:1]
	v_and_b32_e32 v5, 0xffff0000, v13
	v_lshlrev_b32_e32 v4, 16, v13
	v_pk_fma_f32 v[0:1], v[28:29], v[4:5], v[0:1]
	v_and_b32_e32 v9, 0xffff0000, v6
	v_mul_f32_e32 v4, 0xbfb8aa3b, v0
	v_mul_f32_e32 v5, 0xbfb8aa3b, v1
	v_exp_f32_e32 v4, v4
	v_exp_f32_e32 v5, v5
	v_add_f32_e32 v4, 1.0, v4
	v_add_f32_e32 v5, 1.0, v5
	v_rcp_f32_e32 v4, v4
	v_rcp_f32_e32 v5, v5
	s_nop 0
	v_pk_mul_f32 v[0:1], v[0:1], v[4:5]
	s_nop 0
	v_pk_mul_f32 v[4:5], v[0:1], v[0:1]
	s_nop 0
	v_add_f32_e32 v4, v4, v8
	v_add_f32_e32 v12, v5, v4
	v_and_b32_e32 v5, 0xffff0000, v2
	v_lshlrev_b32_e32 v4, 16, v2
	v_pk_fma_f32 v[4:5], v[56:57], v[4:5], 0 op_sel_hi:[1,1,0]
	v_lshlrev_b32_e32 v8, 16, v6
	v_pk_fma_f32 v[4:5], v[64:65], v[8:9], v[4:5]
	v_and_b32_e32 v9, 0xffff0000, v10
	v_lshlrev_b32_e32 v8, 16, v10
	v_pk_fma_f32 v[4:5], v[72:73], v[8:9], v[4:5]
	v_and_b32_e32 v9, 0xffff0000, v14
	v_lshlrev_b32_e32 v8, 16, v14
	v_pk_fma_f32 v[4:5], v[20:21], v[8:9], v[4:5]
	v_lshlrev_b32_e32 v6, 16, v11
	v_mul_f32_e32 v2, 0xbfb8aa3b, v4
	v_exp_f32_e32 v2, v2
	s_nop 0
	v_add_f32_e32 v2, 1.0, v2
	v_rcp_f32_e32 v8, v2
	v_mul_f32_e32 v2, 0xbfb8aa3b, v5
	v_exp_f32_e32 v2, v2
	s_nop 0
	v_add_f32_e32 v2, 1.0, v2
	v_rcp_f32_e32 v9, v2
	s_nop 0
	v_pk_mul_f32 v[4:5], v[4:5], v[8:9]
	s_nop 0
	v_pk_mul_f32 v[8:9], v[4:5], v[4:5]
	s_nop 0
	v_add_f32_e32 v2, v8, v12
	v_add_f32_e32 v10, v9, v2
	v_and_b32_e32 v9, 0xffff0000, v3
	v_lshlrev_b32_e32 v8, 16, v3
	v_pk_fma_f32 v[2:3], v[54:55], v[8:9], 0 op_sel_hi:[1,1,0]
	v_and_b32_e32 v9, 0xffff0000, v7
	v_lshlrev_b32_e32 v8, 16, v7
	v_pk_fma_f32 v[2:3], v[60:61], v[8:9], v[2:3]
	v_and_b32_e32 v7, 0xffff0000, v11
	v_pk_fma_f32 v[2:3], v[68:69], v[6:7], v[2:3]
	v_and_b32_e32 v7, 0xffff0000, v15
	v_lshlrev_b32_e32 v6, 16, v15
	v_pk_fma_f32 v[2:3], v[18:19], v[6:7], v[2:3]
	v_add_u32_e32 v8, 64, v111
	v_mul_f32_e32 v6, 0xbfb8aa3b, v3
	v_exp_f32_e32 v6, v6
	s_nop 0
	v_add_f32_e32 v6, 1.0, v6
	v_rcp_f32_e32 v7, v6
	v_mul_f32_e32 v6, 0xbfb8aa3b, v2
	v_exp_f32_e32 v6, v6
	s_nop 0
	v_add_f32_e32 v6, 1.0, v6
	v_rcp_f32_e32 v6, v6
	s_nop 0
	v_pk_mul_f32 v[2:3], v[2:3], v[6:7]
	s_nop 0
	v_pk_mul_f32 v[6:7], v[2:3], v[2:3]
	s_nop 0
	v_add_f32_e32 v6, v6, v10
	v_add_f32_e32 v6, v7, v6
	v_xor_b32_e32 v7, 1, v234
	v_cmp_lt_i32_e32 vcc, v7, v8
	s_nop 1
	v_cndmask_b32_e32 v7, v234, v7, vcc
	v_lshlrev_b32_e32 v45, 2, v7
	ds_bpermute_b32 v7, v45, v6
	s_waitcnt lgkmcnt(0)
	v_add_f32_e32 v6, v6, v7
	v_xor_b32_e32 v7, 2, v234
	v_cmp_lt_i32_e32 vcc, v7, v8
	s_nop 1
	v_cndmask_b32_e32 v7, v234, v7, vcc
	v_lshlrev_b32_e32 v112, 2, v7
	ds_bpermute_b32 v7, v112, v6
	s_waitcnt lgkmcnt(0)
	v_add_f32_e32 v6, v6, v7
	v_xor_b32_e32 v7, 4, v234
	v_cmp_lt_i32_e32 vcc, v7, v8
	s_nop 1
	v_cndmask_b32_e32 v7, v234, v7, vcc
	v_lshlrev_b32_e32 v113, 2, v7
	ds_bpermute_b32 v7, v113, v6
	s_waitcnt lgkmcnt(0)
	v_add_f32_e32 v6, v6, v7
	v_add_f32_e32 v6, 0x358637bd, v6
	v_cmp_gt_f32_e32 vcc, s33, v6
	v_mul_f32_e32 v7, 0x4b800000, v6
	s_nop 0
	v_cndmask_b32_e32 v6, v6, v7, vcc
	v_rsq_f32_e32 v6, v6
	s_nop 0
	v_mul_f32_e32 v7, 0x45800000, v6
	v_cndmask_b32_e32 v6, v6, v7, vcc
	v_mul_f32_e32 v6, 0x3db504f3, v6
	v_mul_f32_e32 v7, v30, v6
	v_mul_f32_e32 v8, v31, v6
	v_mul_f32_e32 v9, v32, v6
	v_mul_f32_e32 v10, v33, v6
	v_mul_f32_e32 v11, v34, v6
	v_mul_f32_e32 v12, v35, v6
	v_mul_f32_e32 v13, v36, v6
	v_mul_f32_e32 v14, v37, v6
	v_mul_f32_e32 v15, v22, v6
	v_mul_f32_e32 v18, v23, v6
	v_mul_f32_e32 v0, v0, v6
	v_mul_f32_e32 v1, v1, v6
	v_mul_f32_e32 v4, v4, v6
	v_mul_f32_e32 v5, v5, v6
	v_mul_f32_e32 v2, v2, v6
	v_mul_f32_e32 v3, v3, v6
	v_lshlrev_b32_e32 v6, 5, v105
	v_add3_u32 v43, 0, v6, v109
	v_cvt_pk_bf16_f32 v6, v7, v8
	v_add_u32_e32 v8, 0x4400, v43
	v_cvt_pk_bf16_f32 v7, v9, v10
	ds_write2_b32 v8, v6, v7 offset1:1
	v_cvt_pk_bf16_f32 v6, v11, v12
	v_cvt_pk_bf16_f32 v0, v0, v1
	v_cvt_pk_bf16_f32 v7, v13, v14
	ds_write2_b32 v8, v6, v7 offset0:2 offset1:3
	v_cvt_pk_bf16_f32 v6, v15, v18
	ds_write2_b32 v8, v6, v0 offset0:4 offset1:5
	v_cvt_pk_bf16_f32 v0, v4, v5
	v_cvt_pk_bf16_f32 v1, v2, v3
	ds_write2_b32 v8, v0, v1 offset0:6 offset1:7
	s_waitcnt vmcnt(0)
	s_nop 1
	v_mov_b64_e32 v[30:31], v[208:209]
	v_mov_b64_e32 v[32:33], v[210:211]
	v_mov_b64_e32 v[12:13], v[212:213]
	v_mov_b64_e32 v[14:15], v[214:215]
	v_mov_b64_e32 v[26:27], v[216:217]
	v_mov_b64_e32 v[28:29], v[218:219]
	v_mov_b64_e32 v[8:9], v[220:221]
	v_mov_b64_e32 v[10:11], v[222:223]
	v_mov_b64_e32 v[22:23], v[224:225]
	v_mov_b64_e32 v[24:25], v[226:227]
	v_mov_b64_e32 v[4:5], v[240:241]
	v_mov_b64_e32 v[6:7], v[242:243]
	v_mov_b64_e32 v[18:19], v[244:245]
	v_mov_b64_e32 v[20:21], v[246:247]
	v_mov_b64_e32 v[0:1], v[248:249]
	v_mov_b64_e32 v[2:3], v[250:251]
	s_mov_b32 s8, 0
	s_ashr_i32 s9, s8, 31
	s_lshl_b64 s[8:9], s[8:9], 3
	s_add_u32 s8, s0, s8
	s_addc_u32 s9, s1, s9
	s_load_dwordx2 s[8:9], s[8:9], 0x90
	s_waitcnt lgkmcnt(0)
	s_add_u32 s98, s8, s16
	s_addc_u32 s99, s9, s17
	s_add_u32 s100, s8, s18
	s_addc_u32 s101, s9, s19
	s_add_u32 s30, s8, s22
	s_addc_u32 s31, s9, s23
	s_add_u32 s8, s8, s15
	s_addc_u32 s9, s9, s14
	global_load_dwordx4 v[58:61], v41, s[8:9] offset:2096
	global_load_dwordx4 v[62:65], v41, s[8:9] offset:2080
	global_load_dwordx4 v[34:37], v41, s[8:9] offset:2064
	global_load_dwordx4 v[54:57], v41, s[8:9] offset:2048
	global_load_dwordx4 v[140:143], v41, s[98:99] offset:2096
	global_load_dwordx4 v[144:147], v41, s[98:99] offset:2080
	global_load_dwordx4 v[148:151], v41, s[98:99] offset:2064
	global_load_dwordx4 v[152:155], v41, s[98:99] offset:2048
	global_load_dwordx4 v[156:159], v41, s[100:101] offset:2096
	global_load_dwordx4 v[160:163], v41, s[100:101] offset:2080
	global_load_dwordx4 v[164:167], v41, s[100:101] offset:2064
	global_load_dwordx4 v[168:171], v41, s[100:101] offset:2048
	global_load_dwordx4 v[172:175], v41, s[30:31] offset:2096
	global_load_dwordx4 v[176:179], v41, s[30:31] offset:2080
	global_load_dwordx4 v[180:183], v41, s[30:31] offset:2064
	global_load_dwordx4 v[184:187], v41, s[30:31] offset:2048
	global_load_dwordx4 v[208:211], v[138:139], off offset:1024
	global_load_dwordx4 v[212:215], v[138:139], off offset:1040
	global_load_dwordx4 v[216:219], v[194:195], off offset:1024
	global_load_dwordx4 v[220:223], v[194:195], off offset:1040
	global_load_dwordx4 v[224:227], v[196:197], off offset:1024
	global_load_dwordx4 v[240:243], v[196:197], off offset:1040
	global_load_dwordx4 v[244:247], v[252:253], off offset:1024
	global_load_dwordx4 v[248:251], v[252:253], off offset:1040
	s_mov_b32 s8, 0
	s_ashr_i32 s9, s8, 31
	s_lshl_b64 s[8:9], s[8:9], 3
	s_add_u32 s8, s0, s8
	s_addc_u32 s9, s1, s9
	s_waitcnt lgkmcnt(0)
	s_add_u32 s8, s8, s16
	s_addc_u32 s9, s9, s17
	s_waitcnt vmcnt(8)
	v_pk_mul_f32 v[92:93], v[44:45], v[60:61] op_sel_hi:[0,1]
	v_pk_mul_f32 v[74:75], v[44:45], v[58:59] op_sel_hi:[0,1]
	v_pk_mul_f32 v[66:67], v[44:45], v[34:35] op_sel_hi:[0,1]
	v_pk_mul_f32 v[78:79], v[44:45], v[54:55] op_sel_hi:[0,1]
	v_pk_mul_f32 v[34:35], v[44:45], v[64:65] op_sel_hi:[0,1]
	v_pk_mul_f32 v[54:55], v[44:45], v[62:63] op_sel_hi:[0,1]
	v_mov_b64_e32 v[82:83], v[140:141]
	v_mov_b64_e32 v[84:85], v[142:143]
	v_mov_b64_e32 v[58:59], v[144:145]
	v_mov_b64_e32 v[60:61], v[146:147]
	v_mov_b64_e32 v[88:89], v[148:149]
	v_mov_b64_e32 v[90:91], v[150:151]
	v_mov_b64_e32 v[62:63], v[152:153]
	v_mov_b64_e32 v[64:65], v[154:155]
	s_mov_b32 s8, 0
	s_ashr_i32 s9, s8, 31
	s_lshl_b64 s[8:9], s[8:9], 3
	s_add_u32 s8, s0, s8
	s_addc_u32 s9, s1, s9
	v_pk_mul_f32 v[70:71], v[44:45], v[56:57] op_sel_hi:[0,1]
	v_pk_mul_f32 v[56:57], v[44:45], v[36:37] op_sel_hi:[0,1]
	s_waitcnt lgkmcnt(0)
	s_add_u32 s8, s8, s18
	s_addc_u32 s9, s9, s19
	v_mov_b64_e32 v[100:101], v[156:157]
	v_mov_b64_e32 v[102:103], v[158:159]
	v_mov_b64_e32 v[114:115], v[160:161]
	v_mov_b64_e32 v[116:117], v[162:163]
	v_mov_b64_e32 v[118:119], v[164:165]
	v_mov_b64_e32 v[120:121], v[166:167]
	v_mov_b64_e32 v[94:95], v[168:169]
	v_mov_b64_e32 v[96:97], v[170:171]
	s_mov_b32 s8, 0
	s_ashr_i32 s9, s8, 31
	s_lshl_b64 s[8:9], s[8:9], 3
	s_add_u32 s8, s0, s8
	s_addc_u32 s9, s1, s9
	s_waitcnt lgkmcnt(0)
	s_add_u32 s8, s8, s22
	s_addc_u32 s9, s9, s23
	s_waitcnt vmcnt(15)
	v_pk_mul_f32 v[98:99], v[42:43], v[84:85] op_sel_hi:[0,1]
	s_waitcnt vmcnt(14)
	v_pk_mul_f32 v[36:37], v[42:43], v[60:61] op_sel_hi:[0,1]
	v_pk_mul_f32 v[60:61], v[42:43], v[58:59] op_sel_hi:[0,1]
	s_waitcnt vmcnt(12)
	v_pk_mul_f32 v[80:81], v[42:43], v[64:65] op_sel_hi:[0,1]
	v_pk_mul_f32 v[84:85], v[42:43], v[82:83] op_sel_hi:[0,1]
	v_pk_mul_f32 v[86:87], v[42:43], v[62:63] op_sel_hi:[0,1]
	v_pk_mul_f32 v[62:63], v[42:43], v[90:91] op_sel_hi:[0,1]
	v_pk_mul_f32 v[72:73], v[42:43], v[88:89] op_sel_hi:[0,1]
	s_waitcnt vmcnt(11)
	v_pk_mul_f32 v[130:131], v[40:41], v[100:101] op_sel_hi:[0,1]
	s_waitcnt vmcnt(10)
	v_pk_mul_f32 v[58:59], v[40:41], v[116:117] op_sel_hi:[0,1]
	s_waitcnt vmcnt(9)
	v_pk_mul_f32 v[68:69], v[40:41], v[120:121] op_sel_hi:[0,1]
	v_pk_mul_f32 v[82:83], v[40:41], v[118:119] op_sel_hi:[0,1]
	v_pk_mul_f32 v[64:65], v[40:41], v[114:115] op_sel_hi:[0,1]
	v_mov_b64_e32 v[114:115], v[172:173]
	v_mov_b64_e32 v[116:117], v[174:175]
	v_mov_b64_e32 v[118:119], v[176:177]
	v_mov_b64_e32 v[120:121], v[178:179]
	v_mov_b64_e32 v[122:123], v[180:181]
	v_mov_b64_e32 v[124:125], v[182:183]
	v_mov_b64_e32 v[126:127], v[184:185]
	v_mov_b64_e32 v[128:129], v[186:187]
	v_pk_mul_f32 v[102:103], v[40:41], v[102:103] op_sel_hi:[0,1]
	s_waitcnt vmcnt(12)
	v_pk_mul_f32 v[88:89], v[40:41], v[96:97] op_sel_hi:[0,1]
	v_pk_mul_f32 v[96:97], v[40:41], v[94:95] op_sel_hi:[0,1]
	s_waitcnt vmcnt(11)
	v_pk_mul_f32 v[114:115], v[38:39], v[114:115] op_sel_hi:[0,1]
	s_waitcnt vmcnt(10)
	v_pk_mul_f32 v[90:91], v[38:39], v[118:119] op_sel_hi:[0,1]
	v_and_b32_e32 v119, 0xffff0000, v14
	v_lshlrev_b32_e32 v118, 16, v14
	v_pk_fma_f32 v[74:75], v[74:75], v[118:119], 0 op_sel_hi:[1,1,0]
	v_and_b32_e32 v119, 0xffff0000, v10
	v_lshlrev_b32_e32 v118, 16, v10
	v_pk_fma_f32 v[74:75], v[84:85], v[118:119], v[74:75]
	v_and_b32_e32 v85, 0xffff0000, v6
	v_lshlrev_b32_e32 v84, 16, v6
	v_pk_fma_f32 v[74:75], v[130:131], v[84:85], v[74:75]
	v_and_b32_e32 v85, 0xffff0000, v2
	v_lshlrev_b32_e32 v84, 16, v2
	v_pk_fma_f32 v[74:75], v[114:115], v[84:85], v[74:75]
	v_and_b32_e32 v115, 0xffff0000, v15
	v_mul_f32_e32 v2, 0xbfb8aa3b, v74
	v_exp_f32_e32 v2, v2
	v_lshlrev_b32_e32 v114, 16, v15
	v_pk_fma_f32 v[14:15], v[92:93], v[114:115], 0 op_sel_hi:[1,1,0]
	v_and_b32_e32 v93, 0xffff0000, v11
	v_add_f32_e32 v2, 1.0, v2
	v_rcp_f32_e32 v84, v2
	v_mul_f32_e32 v2, 0xbfb8aa3b, v75
	v_exp_f32_e32 v2, v2
	v_lshlrev_b32_e32 v92, 16, v11
	v_pk_fma_f32 v[10:11], v[98:99], v[92:93], v[14:15]
	v_and_b32_e32 v15, 0xffff0000, v7
	v_lshlrev_b32_e32 v14, 16, v7
	v_pk_mul_f32 v[116:117], v[38:39], v[116:117] op_sel_hi:[0,1]
	v_add_f32_e32 v2, 1.0, v2
	v_pk_fma_f32 v[6:7], v[102:103], v[14:15], v[10:11]
	v_and_b32_e32 v11, 0xffff0000, v3
	v_lshlrev_b32_e32 v10, 16, v3
	v_rcp_f32_e32 v85, v2
	v_pk_fma_f32 v[2:3], v[116:117], v[10:11], v[6:7]
	v_lshlrev_b32_e32 v10, 16, v30
	v_and_b32_e32 v11, 0xffff0000, v30
	v_lshlrev_b32_e32 v30, 16, v31
	v_and_b32_e32 v31, 0xffff0000, v31
	v_pk_fma_f32 v[10:11], v[78:79], v[10:11], 0 op_sel_hi:[1,1,0]
	v_lshlrev_b32_e32 v14, 16, v26
	v_and_b32_e32 v15, 0xffff0000, v26
	v_pk_fma_f32 v[30:31], v[70:71], v[30:31], 0 op_sel_hi:[1,1,0]
	v_lshlrev_b32_e32 v26, 16, v27
	v_and_b32_e32 v27, 0xffff0000, v27
	v_pk_fma_f32 v[10:11], v[86:87], v[14:15], v[10:11]
	v_lshlrev_b32_e32 v14, 16, v22
	v_and_b32_e32 v15, 0xffff0000, v22
	v_pk_fma_f32 v[26:27], v[80:81], v[26:27], v[30:31]
	v_lshlrev_b32_e32 v22, 16, v23
	v_and_b32_e32 v23, 0xffff0000, v23
	s_waitcnt vmcnt(8)
	v_pk_mul_f32 v[128:129], v[38:39], v[128:129] op_sel_hi:[0,1]
	v_pk_fma_f32 v[10:11], v[96:97], v[14:15], v[10:11]
	v_lshlrev_b32_e32 v14, 16, v18
	v_and_b32_e32 v15, 0xffff0000, v18
	v_pk_fma_f32 v[22:23], v[88:89], v[22:23], v[26:27]
	v_lshlrev_b32_e32 v18, 16, v19
	v_and_b32_e32 v19, 0xffff0000, v19
	v_pk_fma_f32 v[18:19], v[128:129], v[18:19], v[22:23]
	v_lshlrev_b32_e32 v26, 16, v32
	v_mul_f32_e32 v16, 0xbfb8aa3b, v18
	v_exp_f32_e32 v16, v16
	v_and_b32_e32 v27, 0xffff0000, v32
	v_pk_fma_f32 v[26:27], v[66:67], v[26:27], 0 op_sel_hi:[1,1,0]
	v_lshlrev_b32_e32 v30, 16, v28
	v_add_f32_e32 v16, 1.0, v16
	v_rcp_f32_e32 v22, v16
	v_mul_f32_e32 v16, 0xbfb8aa3b, v19
	v_exp_f32_e32 v16, v16
	v_and_b32_e32 v31, 0xffff0000, v28
	v_pk_fma_f32 v[26:27], v[72:73], v[30:31], v[26:27]
	v_lshlrev_b32_e32 v30, 16, v24
	v_and_b32_e32 v31, 0xffff0000, v24
	v_pk_mul_f32 v[100:101], v[38:39], v[122:123] op_sel_hi:[0,1]
	v_pk_fma_f32 v[26:27], v[82:83], v[30:31], v[26:27]
	v_lshlrev_b32_e32 v30, 16, v20
	v_and_b32_e32 v31, 0xffff0000, v20
	v_add_f32_e32 v16, 1.0, v16
	v_pk_fma_f32 v[26:27], v[100:101], v[30:31], v[26:27]
	v_rcp_f32_e32 v23, v16
	v_mul_f32_e32 v16, 0xbfb8aa3b, v26
	v_lshlrev_b32_e32 v32, 16, v33
	v_and_b32_e32 v33, 0xffff0000, v33
	v_exp_f32_e32 v16, v16
	v_pk_fma_f32 v[32:33], v[56:57], v[32:33], 0 op_sel_hi:[1,1,0]
	v_lshlrev_b32_e32 v28, 16, v29
	v_and_b32_e32 v29, 0xffff0000, v29
	v_pk_fma_f32 v[28:29], v[62:63], v[28:29], v[32:33]
	v_lshlrev_b32_e32 v24, 16, v25
	v_and_b32_e32 v25, 0xffff0000, v25
	v_pk_fma_f32 v[24:25], v[68:69], v[24:25], v[28:29]
	v_lshlrev_b32_e32 v28, 16, v12
	v_and_b32_e32 v29, 0xffff0000, v12
	v_pk_fma_f32 v[28:29], v[54:55], v[28:29], 0 op_sel_hi:[1,1,0]
	v_lshlrev_b32_e32 v32, 16, v8
	v_and_b32_e32 v33, 0xffff0000, v8
	v_add_f32_e32 v16, 1.0, v16
	v_pk_fma_f32 v[28:29], v[60:61], v[32:33], v[28:29]
	v_lshlrev_b32_e32 v32, 16, v4
	v_and_b32_e32 v33, 0xffff0000, v4
	v_rcp_f32_e32 v30, v16
	v_mul_f32_e32 v16, 0xbfb8aa3b, v27
	v_pk_fma_f32 v[28:29], v[64:65], v[32:33], v[28:29]
	v_lshlrev_b32_e32 v32, 16, v0
	v_and_b32_e32 v33, 0xffff0000, v0
	v_exp_f32_e32 v16, v16
	v_pk_fma_f32 v[28:29], v[90:91], v[32:33], v[28:29]
	v_pk_mul_f32 v[94:95], v[38:39], v[124:125] op_sel_hi:[0,1]
	v_mul_f32_e32 v0, 0xbfb8aa3b, v28
	v_exp_f32_e32 v0, v0
	v_lshlrev_b32_e32 v20, 16, v21
	v_and_b32_e32 v21, 0xffff0000, v21
	v_pk_mul_f32 v[126:127], v[38:39], v[126:127] op_sel_hi:[0,1]
	v_add_f32_e32 v16, 1.0, v16
	v_pk_fma_f32 v[20:21], v[94:95], v[20:21], v[24:25]
	v_pk_fma_f32 v[10:11], v[126:127], v[14:15], v[10:11]
	v_rcp_f32_e32 v31, v16
	v_mul_f32_e32 v16, 0xbfb8aa3b, v20
	v_mul_f32_e32 v14, 0xbfb8aa3b, v10
	v_mul_f32_e32 v15, 0xbfb8aa3b, v11
	v_exp_f32_e32 v16, v16
	v_add_f32_e32 v0, 1.0, v0
	v_exp_f32_e32 v14, v14
	v_exp_f32_e32 v15, v15
	v_rcp_f32_e32 v32, v0
	v_mul_f32_e32 v0, 0xbfb8aa3b, v29
	v_exp_f32_e32 v0, v0
	v_add_f32_e32 v16, 1.0, v16
	v_lshlrev_b32_e32 v12, 16, v13
	v_and_b32_e32 v13, 0xffff0000, v13
	v_add_f32_e32 v14, 1.0, v14
	v_add_f32_e32 v15, 1.0, v15
	v_rcp_f32_e32 v24, v16
	v_mul_f32_e32 v16, 0xbfb8aa3b, v21
	v_pk_fma_f32 v[12:13], v[34:35], v[12:13], 0 op_sel_hi:[1,1,0]
	v_lshlrev_b32_e32 v8, 16, v9
	v_and_b32_e32 v9, 0xffff0000, v9
	v_rcp_f32_e32 v14, v14
	v_rcp_f32_e32 v15, v15
	v_exp_f32_e32 v16, v16
	v_add_f32_e32 v0, 1.0, v0
	v_pk_fma_f32 v[8:9], v[36:37], v[8:9], v[12:13]
	v_lshlrev_b32_e32 v4, 16, v5
	v_and_b32_e32 v5, 0xffff0000, v5
	v_pk_mul_f32 v[76:77], v[38:39], v[120:121] op_sel_hi:[0,1]
	v_mul_f32_e32 v6, 0xbfb8aa3b, v3
	v_rcp_f32_e32 v33, v0
	v_pk_fma_f32 v[4:5], v[58:59], v[4:5], v[8:9]
	v_lshlrev_b32_e32 v0, 16, v1
	v_and_b32_e32 v1, 0xffff0000, v1
	v_exp_f32_e32 v6, v6
	v_pk_fma_f32 v[0:1], v[76:77], v[0:1], v[4:5]
	v_pk_mul_f32 v[10:11], v[10:11], v[14:15]
	v_mul_f32_e32 v4, 0xbfb8aa3b, v0
	v_mul_f32_e32 v5, 0xbfb8aa3b, v1
	v_add_f32_e32 v16, 1.0, v16
	v_exp_f32_e32 v4, v4
	v_exp_f32_e32 v5, v5
	v_pk_mul_f32 v[14:15], v[10:11], v[10:11]
	v_pk_mul_f32 v[18:19], v[18:19], v[22:23]
	v_rcp_f32_e32 v25, v16
	v_add_f32_e32 v6, 1.0, v6
	v_pk_mul_f32 v[22:23], v[18:19], v[18:19]
	v_add_f32_e32 v8, v14, v15
	v_rcp_f32_e32 v7, v6
	v_mul_f32_e32 v6, 0xbfb8aa3b, v2
	v_pk_mul_f32 v[26:27], v[26:27], v[30:31]
	v_add_f32_e32 v8, v22, v8
	v_exp_f32_e32 v6, v6
	v_pk_mul_f32 v[30:31], v[26:27], v[26:27]
	v_add_f32_e32 v4, 1.0, v4
	v_add_f32_e32 v5, 1.0, v5
	v_add_f32_e32 v8, v23, v8
	v_pk_mul_f32 v[20:21], v[20:21], v[24:25]
	v_rcp_f32_e32 v4, v4
	v_rcp_f32_e32 v5, v5
	v_add_f32_e32 v8, v30, v8
	v_pk_mul_f32 v[24:25], v[20:21], v[20:21]
	v_add_f32_e32 v8, v31, v8
	v_pk_mul_f32 v[28:29], v[28:29], v[32:33]
	v_add_f32_e32 v8, v24, v8
	v_add_f32_e32 v6, 1.0, v6
	v_pk_mul_f32 v[32:33], v[28:29], v[28:29]
	v_add_f32_e32 v8, v25, v8
	v_rcp_f32_e32 v6, v6
	v_pk_mul_f32 v[0:1], v[0:1], v[4:5]
	v_add_f32_e32 v8, v32, v8
	v_pk_mul_f32 v[4:5], v[0:1], v[0:1]
	v_add_f32_e32 v8, v33, v8
	v_pk_mul_f32 v[74:75], v[74:75], v[84:85]
	v_add_f32_e32 v4, v4, v8
	v_pk_mul_f32 v[84:85], v[74:75], v[74:75]
	v_add_f32_e32 v4, v5, v4
	v_pk_mul_f32 v[2:3], v[2:3], v[6:7]
	v_add_f32_e32 v4, v84, v4
	v_pk_mul_f32 v[6:7], v[2:3], v[2:3]
	v_add_f32_e32 v4, v85, v4
	v_add_f32_e32 v4, v6, v4
	v_add_f32_e32 v4, v7, v4
	ds_bpermute_b32 v5, v45, v4
	v_or_b32_e32 v34, 0x400, v39
	s_waitcnt lgkmcnt(0)
	v_add_f32_e32 v4, v4, v5
	ds_bpermute_b32 v5, v112, v4
	s_waitcnt lgkmcnt(0)
	v_add_f32_e32 v4, v4, v5
	ds_bpermute_b32 v5, v113, v4
	s_waitcnt lgkmcnt(0)
	v_add_f32_e32 v4, v4, v5
	v_add_f32_e32 v4, 0x358637bd, v4
	v_cmp_gt_f32_e32 vcc, s33, v4
	v_mul_f32_e32 v5, 0x4b800000, v4
	s_nop 0
	v_cndmask_b32_e32 v4, v4, v5, vcc
	v_rsq_f32_e32 v4, v4
	s_nop 0
	v_mul_f32_e32 v5, 0x45800000, v4
	v_cndmask_b32_e32 v16, v4, v5, vcc
	v_pk_mul_f32 v[4:5], v[10:11], v[16:17] op_sel_hi:[1,0]
	v_pk_mul_f32 v[6:7], v[18:19], v[16:17] op_sel_hi:[1,0]
	v_pk_mul_f32 v[8:9], v[26:27], v[16:17] op_sel_hi:[1,0]
	v_pk_mul_f32 v[10:11], v[20:21], v[16:17] op_sel_hi:[1,0]
	v_pk_mul_f32 v[12:13], v[28:29], v[16:17] op_sel_hi:[1,0]
	v_pk_mul_f32 v[14:15], v[0:1], v[16:17] op_sel_hi:[1,0]
	v_pk_mul_f32 v[0:1], v[74:75], v[16:17] op_sel_hi:[1,0]
	v_pk_mul_f32 v[2:3], v[2:3], v[16:17] op_sel_hi:[1,0]
	v_cvt_pk_bf16_f32 v16, v4, v5
	v_cvt_pk_bf16_f32 v18, v6, v7
	ds_write2_b32 v43, v16, v18 offset1:1
	v_cvt_pk_bf16_f32 v16, v8, v9
	v_cvt_pk_bf16_f32 v18, v10, v11
	ds_write2_b32 v43, v16, v18 offset0:2 offset1:3
	v_cvt_pk_bf16_f32 v16, v12, v13
	v_cvt_pk_bf16_f32 v18, v14, v15
	ds_write2_b32 v43, v16, v18 offset0:4 offset1:5
	v_cvt_pk_bf16_f32 v16, v0, v1
	v_cvt_pk_bf16_f32 v18, v2, v3
	ds_write2_b32 v43, v16, v18 offset0:6 offset1:7
	ds_write_b128 v110, v[4:7] offset:35328
	ds_write_b128 v110, v[8:11] offset:35344
	ds_write_b128 v110, v[12:15] offset:35360
	ds_write_b128 v110, v[0:3] offset:35376
	s_waitcnt vmcnt(0)
	s_nop 1
	v_mov_b64_e32 v[12:13], v[208:209]
	v_mov_b64_e32 v[14:15], v[210:211]
	v_mov_b64_e32 v[30:31], v[212:213]
	v_mov_b64_e32 v[32:33], v[214:215]
	v_mov_b64_e32 v[8:9], v[216:217]
	v_mov_b64_e32 v[10:11], v[218:219]
	v_mov_b64_e32 v[26:27], v[220:221]
	v_mov_b64_e32 v[28:29], v[222:223]
	v_mov_b64_e32 v[4:5], v[224:225]
	v_mov_b64_e32 v[6:7], v[226:227]
	v_mov_b64_e32 v[22:23], v[240:241]
	v_mov_b64_e32 v[24:25], v[242:243]
	v_mov_b64_e32 v[0:1], v[244:245]
	v_mov_b64_e32 v[2:3], v[246:247]
	v_mov_b64_e32 v[18:19], v[248:249]
	v_mov_b64_e32 v[20:21], v[250:251]
	s_mov_b32 s8, 0
	s_ashr_i32 s9, s8, 31
	s_lshl_b64 s[8:9], s[8:9], 3
	s_add_u32 s8, s0, s8
	s_addc_u32 s9, s1, s9
	s_load_dwordx2 s[8:9], s[8:9], 0x90
	v_lshlrev_b32_e32 v16, 2, v34
	v_cmp_gt_u32_e32 vcc, 64, v106
	s_waitcnt lgkmcnt(0)
	s_add_u32 s98, s8, s16
	s_addc_u32 s99, s9, s17
	s_add_u32 s100, s8, s18
	s_addc_u32 s101, s9, s19
	s_add_u32 s30, s8, s22
	s_addc_u32 s31, s9, s23
	s_add_u32 s8, s8, s15
	s_addc_u32 s9, s9, s14
	global_load_dwordx4 v[52:55], v16, s[8:9] offset:48
	global_load_dwordx4 v[56:59], v16, s[8:9] offset:32
	global_load_dwordx4 v[48:51], v16, s[8:9] offset:16
	global_load_dwordx4 v[34:37], v16, s[8:9]
	global_load_dwordx4 v[140:143], v16, s[98:99] offset:48
	global_load_dwordx4 v[144:147], v16, s[98:99] offset:32
	global_load_dwordx4 v[148:151], v16, s[98:99] offset:16
	global_load_dwordx4 v[152:155], v16, s[98:99]
	global_load_dwordx4 v[156:159], v16, s[100:101] offset:48
	global_load_dwordx4 v[160:163], v16, s[100:101] offset:32
	global_load_dwordx4 v[164:167], v16, s[100:101] offset:16
	global_load_dwordx4 v[168:171], v16, s[100:101]
	global_load_dwordx4 v[172:175], v16, s[30:31] offset:48
	global_load_dwordx4 v[176:179], v16, s[30:31] offset:32
	global_load_dwordx4 v[180:183], v16, s[30:31] offset:16
	global_load_dwordx4 v[184:187], v16, s[30:31]
	s_mov_b32 s8, 0
	s_ashr_i32 s9, s8, 31
	s_lshl_b64 s[8:9], s[8:9], 3
	s_add_u32 s8, s0, s8
	s_addc_u32 s9, s1, s9
	s_waitcnt lgkmcnt(0)
	s_add_u32 s8, s8, s16
	s_addc_u32 s9, s9, s17
	s_waitcnt vmcnt(0)
	v_pk_mul_f32 v[70:71], v[44:45], v[52:53] op_sel_hi:[0,1]
	v_pk_mul_f32 v[56:57], v[44:45], v[56:57] op_sel_hi:[0,1]
	v_pk_mul_f32 v[48:49], v[44:45], v[48:49] op_sel_hi:[0,1]
	v_pk_mul_f32 v[34:35], v[44:45], v[34:35] op_sel_hi:[0,1]
	v_pk_mul_f32 v[36:37], v[44:45], v[36:37] op_sel_hi:[0,1]
	v_pk_mul_f32 v[50:51], v[44:45], v[50:51] op_sel_hi:[0,1]
	v_pk_mul_f32 v[62:63], v[44:45], v[58:59] op_sel_hi:[0,1]
	v_pk_mul_f32 v[78:79], v[44:45], v[54:55] op_sel_hi:[0,1]
	v_mov_b64_e32 v[66:67], v[140:141]
	v_mov_b64_e32 v[68:69], v[142:143]
	v_mov_b64_e32 v[72:73], v[144:145]
	v_mov_b64_e32 v[74:75], v[146:147]
	v_mov_b64_e32 v[58:59], v[148:149]
	v_mov_b64_e32 v[60:61], v[150:151]
	v_mov_b64_e32 v[44:45], v[152:153]
	v_mov_b64_e32 v[46:47], v[154:155]
	s_mov_b32 s8, 0
	s_ashr_i32 s9, s8, 31
	s_lshl_b64 s[8:9], s[8:9], 3
	s_add_u32 s8, s0, s8
	s_addc_u32 s9, s1, s9
	s_waitcnt lgkmcnt(0)
	s_add_u32 s8, s8, s18
	s_addc_u32 s9, s9, s19
	s_waitcnt vmcnt(3)
	v_pk_mul_f32 v[80:81], v[42:43], v[66:67] op_sel_hi:[0,1]
	s_waitcnt vmcnt(2)
	v_pk_mul_f32 v[64:65], v[42:43], v[72:73] op_sel_hi:[0,1]
	v_pk_mul_f32 v[72:73], v[42:43], v[74:75] op_sel_hi:[0,1]
	v_pk_mul_f32 v[86:87], v[42:43], v[68:69] op_sel_hi:[0,1]
	v_mov_b64_e32 v[88:89], v[156:157]
	v_mov_b64_e32 v[90:91], v[158:159]
	v_mov_b64_e32 v[74:75], v[160:161]
	v_mov_b64_e32 v[76:77], v[162:163]
	v_mov_b64_e32 v[66:67], v[164:165]
	v_mov_b64_e32 v[68:69], v[166:167]
	v_mov_b64_e32 v[82:83], v[168:169]
	v_mov_b64_e32 v[84:85], v[170:171]
	s_mov_b32 s8, 0
	s_ashr_i32 s9, s8, 31
	s_lshl_b64 s[8:9], s[8:9], 3
	s_add_u32 s8, s0, s8
	s_addc_u32 s9, s1, s9
	s_waitcnt vmcnt(4)
	v_pk_mul_f32 v[44:45], v[42:43], v[44:45] op_sel_hi:[0,1]
	v_pk_mul_f32 v[46:47], v[42:43], v[46:47] op_sel_hi:[0,1]
	v_pk_mul_f32 v[54:55], v[42:43], v[58:59] op_sel_hi:[0,1]
	v_pk_mul_f32 v[58:59], v[42:43], v[60:61] op_sel_hi:[0,1]
	s_waitcnt lgkmcnt(0)
	s_add_u32 s8, s8, s22
	s_addc_u32 s9, s9, s23
	v_mov_b64_e32 v[92:93], v[172:173]
	v_mov_b64_e32 v[94:95], v[174:175]
	v_mov_b64_e32 v[96:97], v[176:177]
	v_mov_b64_e32 v[98:99], v[178:179]
	v_mov_b64_e32 v[100:101], v[180:181]
	v_mov_b64_e32 v[102:103], v[182:183]
	v_mov_b64_e32 v[112:113], v[184:185]
	v_mov_b64_e32 v[114:115], v[186:187]
	s_waitcnt vmcnt(7)
	v_pk_mul_f32 v[88:89], v[40:41], v[88:89] op_sel_hi:[0,1]
	s_waitcnt vmcnt(6)
	v_pk_mul_f32 v[74:75], v[40:41], v[74:75] op_sel_hi:[0,1]
	s_waitcnt vmcnt(5)
	v_pk_mul_f32 v[60:61], v[40:41], v[66:67] op_sel_hi:[0,1]
	s_waitcnt vmcnt(4)
	v_pk_mul_f32 v[42:43], v[40:41], v[82:83] op_sel_hi:[0,1]
	v_pk_mul_f32 v[52:53], v[40:41], v[84:85] op_sel_hi:[0,1]
	v_pk_mul_f32 v[66:67], v[40:41], v[68:69] op_sel_hi:[0,1]
	v_pk_mul_f32 v[82:83], v[40:41], v[76:77] op_sel_hi:[0,1]
	v_pk_mul_f32 v[40:41], v[40:41], v[90:91] op_sel_hi:[0,1]
	s_waitcnt vmcnt(3)
	v_pk_mul_f32 v[92:93], v[38:39], v[92:93] op_sel_hi:[0,1]
	s_waitcnt vmcnt(2)
	v_pk_mul_f32 v[96:97], v[38:39], v[96:97] op_sel_hi:[0,1]
	s_waitcnt vmcnt(1)
	v_pk_mul_f32 v[84:85], v[38:39], v[100:101] op_sel_hi:[0,1]
	s_waitcnt vmcnt(0)
	v_pk_mul_f32 v[68:69], v[38:39], v[112:113] op_sel_hi:[0,1]
	v_pk_mul_f32 v[76:77], v[38:39], v[114:115] op_sel_hi:[0,1]
	v_pk_mul_f32 v[90:91], v[38:39], v[102:103] op_sel_hi:[0,1]
	v_pk_mul_f32 v[98:99], v[38:39], v[98:99] op_sel_hi:[0,1]
	v_pk_mul_f32 v[38:39], v[38:39], v[94:95] op_sel_hi:[0,1]
	v_lshlrev_b32_e32 v94, 16, v33
	v_and_b32_e32 v95, 0xffff0000, v33
	v_pk_fma_f32 v[78:79], v[78:79], v[94:95], 0 op_sel_hi:[1,1,0]
	v_lshlrev_b32_e32 v94, 16, v29
	v_and_b32_e32 v95, 0xffff0000, v29
	v_pk_fma_f32 v[78:79], v[86:87], v[94:95], v[78:79]
	v_lshlrev_b32_e32 v86, 16, v25
	v_and_b32_e32 v87, 0xffff0000, v25
	v_pk_fma_f32 v[40:41], v[40:41], v[86:87], v[78:79]
	v_lshlrev_b32_e32 v78, 16, v21
	v_and_b32_e32 v79, 0xffff0000, v21
	v_pk_fma_f32 v[38:39], v[38:39], v[78:79], v[40:41]
	v_lshlrev_b32_e32 v78, 16, v32
	v_and_b32_e32 v79, 0xffff0000, v32
	v_pk_fma_f32 v[32:33], v[70:71], v[78:79], 0 op_sel_hi:[1,1,0]
	v_lshlrev_b32_e32 v70, 16, v28
	v_and_b32_e32 v71, 0xffff0000, v28
	v_pk_fma_f32 v[28:29], v[80:81], v[70:71], v[32:33]
	v_lshlrev_b32_e32 v32, 16, v24
	v_and_b32_e32 v33, 0xffff0000, v24
	v_pk_fma_f32 v[24:25], v[88:89], v[32:33], v[28:29]
	v_lshlrev_b32_e32 v28, 16, v20
	v_and_b32_e32 v29, 0xffff0000, v20
	v_pk_fma_f32 v[20:21], v[92:93], v[28:29], v[24:25]
	v_lshlrev_b32_e32 v28, 16, v31
	v_and_b32_e32 v29, 0xffff0000, v31
	v_pk_fma_f32 v[28:29], v[62:63], v[28:29], 0 op_sel_hi:[1,1,0]
	v_lshlrev_b32_e32 v62, 16, v30
	v_and_b32_e32 v63, 0xffff0000, v30
	v_pk_fma_f32 v[30:31], v[56:57], v[62:63], 0 op_sel_hi:[1,1,0]
	v_lshlrev_b32_e32 v56, 16, v26
	v_and_b32_e32 v57, 0xffff0000, v26
	v_lshlrev_b32_e32 v32, 16, v27
	v_and_b32_e32 v33, 0xffff0000, v27
	v_pk_fma_f32 v[26:27], v[64:65], v[56:57], v[30:31]
	v_lshlrev_b32_e32 v30, 16, v22
	v_and_b32_e32 v31, 0xffff0000, v22
	v_pk_fma_f32 v[28:29], v[72:73], v[32:33], v[28:29]
	v_lshlrev_b32_e32 v32, 16, v23
	v_and_b32_e32 v33, 0xffff0000, v23
	v_pk_fma_f32 v[22:23], v[74:75], v[30:31], v[26:27]
	v_lshlrev_b32_e32 v26, 16, v18
	v_and_b32_e32 v27, 0xffff0000, v18
	v_pk_fma_f32 v[28:29], v[82:83], v[32:33], v[28:29]
	v_lshlrev_b32_e32 v32, 16, v19
	v_and_b32_e32 v33, 0xffff0000, v19
	v_pk_fma_f32 v[18:19], v[96:97], v[26:27], v[22:23]
	v_lshlrev_b32_e32 v26, 16, v15
	v_and_b32_e32 v27, 0xffff0000, v15
	v_pk_fma_f32 v[26:27], v[50:51], v[26:27], 0 op_sel_hi:[1,1,0]
	v_lshlrev_b32_e32 v50, 16, v14
	v_and_b32_e32 v51, 0xffff0000, v14
	v_mul_f32_e32 v16, 0xbfb8aa3b, v39
	v_lshlrev_b32_e32 v30, 16, v11
	v_and_b32_e32 v31, 0xffff0000, v11
	v_pk_fma_f32 v[14:15], v[48:49], v[50:51], 0 op_sel_hi:[1,1,0]
	v_lshlrev_b32_e32 v48, 16, v10
	v_and_b32_e32 v49, 0xffff0000, v10
	v_exp_f32_e32 v16, v16
	v_pk_fma_f32 v[26:27], v[58:59], v[30:31], v[26:27]
	v_lshlrev_b32_e32 v30, 16, v7
	v_and_b32_e32 v31, 0xffff0000, v7
	v_pk_fma_f32 v[10:11], v[54:55], v[48:49], v[14:15]
	v_lshlrev_b32_e32 v14, 16, v6
	v_and_b32_e32 v15, 0xffff0000, v6
	v_pk_fma_f32 v[26:27], v[66:67], v[30:31], v[26:27]
	v_lshlrev_b32_e32 v30, 16, v3
	v_and_b32_e32 v31, 0xffff0000, v3
	v_pk_fma_f32 v[6:7], v[60:61], v[14:15], v[10:11]
	v_lshlrev_b32_e32 v10, 16, v2
	v_and_b32_e32 v11, 0xffff0000, v2
	v_pk_fma_f32 v[26:27], v[90:91], v[30:31], v[26:27]
	v_pk_fma_f32 v[6:7], v[84:85], v[10:11], v[6:7]
	v_mul_f32_e32 v3, 0xbfb8aa3b, v27
	v_mul_f32_e32 v2, 0xbfb8aa3b, v7
	v_add_f32_e32 v16, 1.0, v16
	v_exp_f32_e32 v3, v3
	v_exp_f32_e32 v2, v2
	v_rcp_f32_e32 v41, v16
	v_mul_f32_e32 v16, 0xbfb8aa3b, v38
	v_exp_f32_e32 v16, v16
	v_add_f32_e32 v3, 1.0, v3
	v_add_f32_e32 v2, 1.0, v2
	v_rcp_f32_e32 v31, v3
	v_mul_f32_e32 v3, 0xbfb8aa3b, v26
	v_rcp_f32_e32 v11, v2
	v_mul_f32_e32 v2, 0xbfb8aa3b, v6
	v_add_f32_e32 v16, 1.0, v16
	v_exp_f32_e32 v3, v3
	v_exp_f32_e32 v2, v2
	v_rcp_f32_e32 v40, v16
	v_mul_f32_e32 v16, 0xbfb8aa3b, v21
	v_exp_f32_e32 v16, v16
	v_add_f32_e32 v3, 1.0, v3
	v_add_f32_e32 v2, 1.0, v2
	v_rcp_f32_e32 v30, v3
	v_rcp_f32_e32 v10, v2
	v_lshlrev_b32_e32 v2, 16, v13
	v_and_b32_e32 v3, 0xffff0000, v13
	v_add_f32_e32 v16, 1.0, v16
	v_pk_fma_f32 v[2:3], v[36:37], v[2:3], 0 op_sel_hi:[1,1,0]
	v_lshlrev_b32_e32 v14, 16, v9
	v_and_b32_e32 v15, 0xffff0000, v9
	v_rcp_f32_e32 v25, v16
	v_mul_f32_e32 v16, 0xbfb8aa3b, v20
	v_pk_fma_f32 v[2:3], v[46:47], v[14:15], v[2:3]
	v_lshlrev_b32_e32 v14, 16, v5
	v_and_b32_e32 v15, 0xffff0000, v5
	v_exp_f32_e32 v16, v16
	v_pk_fma_f32 v[2:3], v[52:53], v[14:15], v[2:3]
	v_lshlrev_b32_e32 v14, 16, v1
	v_and_b32_e32 v15, 0xffff0000, v1
	v_pk_fma_f32 v[2:3], v[76:77], v[14:15], v[2:3]
	v_add_f32_e32 v16, 1.0, v16
	v_mul_f32_e32 v1, 0xbfb8aa3b, v3
	v_exp_f32_e32 v1, v1
	v_pk_fma_f32 v[28:29], v[98:99], v[32:33], v[28:29]
	v_rcp_f32_e32 v24, v16
	v_mul_f32_e32 v16, 0xbfb8aa3b, v29
	v_exp_f32_e32 v16, v16
	v_add_f32_e32 v1, 1.0, v1
	v_rcp_f32_e32 v15, v1
	v_mul_f32_e32 v1, 0xbfb8aa3b, v2
	v_exp_f32_e32 v1, v1
	v_add_f32_e32 v16, 1.0, v16
	v_lshlrev_b32_e32 v36, 16, v12
	v_and_b32_e32 v37, 0xffff0000, v12
	v_rcp_f32_e32 v33, v16
	v_mul_f32_e32 v16, 0xbfb8aa3b, v28
	v_pk_fma_f32 v[12:13], v[34:35], v[36:37], 0 op_sel_hi:[1,1,0]
	v_lshlrev_b32_e32 v34, 16, v8
	v_and_b32_e32 v35, 0xffff0000, v8
	v_exp_f32_e32 v16, v16
	v_pk_fma_f32 v[8:9], v[44:45], v[34:35], v[12:13]
	v_lshlrev_b32_e32 v12, 16, v4
	v_and_b32_e32 v13, 0xffff0000, v4
	v_add_f32_e32 v1, 1.0, v1
	v_pk_fma_f32 v[4:5], v[42:43], v[12:13], v[8:9]
	v_lshlrev_b32_e32 v8, 16, v0
	v_and_b32_e32 v9, 0xffff0000, v0
	v_rcp_f32_e32 v14, v1
	v_pk_fma_f32 v[0:1], v[68:69], v[8:9], v[4:5]
	v_add_f32_e32 v16, 1.0, v16
	v_mul_f32_e32 v4, 0xbfb8aa3b, v1
	v_exp_f32_e32 v4, v4
	v_rcp_f32_e32 v32, v16
	v_mul_f32_e32 v16, 0xbfb8aa3b, v19
	v_exp_f32_e32 v16, v16
	v_add_f32_e32 v4, 1.0, v4
	v_rcp_f32_e32 v5, v4
	v_mul_f32_e32 v4, 0xbfb8aa3b, v0
	v_add_f32_e32 v16, 1.0, v16
	v_exp_f32_e32 v4, v4
	v_rcp_f32_e32 v23, v16
	v_mul_f32_e32 v16, 0xbfb8aa3b, v18
	v_exp_f32_e32 v16, v16
	v_add_f32_e32 v4, 1.0, v4
	v_rcp_f32_e32 v4, v4
	v_pk_mul_f32 v[2:3], v[2:3], v[14:15]
	v_add_f32_e32 v16, 1.0, v16
	v_rcp_f32_e32 v22, v16
	v_pk_mul_f32 v[0:1], v[0:1], v[4:5]
	ds_write_b128 v110, v[0:3] offset:34816
	v_pk_mul_f32 v[0:1], v[6:7], v[10:11]
	v_pk_mul_f32 v[2:3], v[26:27], v[30:31]
	ds_write_b128 v110, v[0:3] offset:34832
	v_pk_mul_f32 v[0:1], v[18:19], v[22:23]
	v_pk_mul_f32 v[2:3], v[28:29], v[32:33]
	ds_write_b128 v110, v[0:3] offset:34848
	v_pk_mul_f32 v[0:1], v[20:21], v[24:25]
	v_pk_mul_f32 v[2:3], v[38:39], v[40:41]
	v_lshl_add_u32 v44, v106, 2, 0
	ds_write_b128 v110, v[0:3] offset:34864
	s_and_saveexec_b64 s[8:9], vcc
	s_cbranch_execz .LBB0_763
	v_or_b32_e32 v0, s5, v106
	v_ashrrev_i32_e32 v1, 31, v0
	v_lshlrev_b64 v[0:1], 5, v[0:1]
	v_lshl_add_u64 v[0:1], s[42:43], 0, v[0:1]
	s_lshl_b32 s52, s37, 2
	v_lshl_add_u64 v[0:1], v[0:1], 0, s[52:53]
	v_mov_b32_e32 v2, v189
	s_nop 0
	v_mov_b32_e32 v0, v190
	s_mov_b32 s38, 0
	s_ashr_i32 s39, s38, 31
	s_lshl_b64 s[38:39], s[38:39], 3
	s_add_u32 s38, s0, s38
	s_addc_u32 s39, s1, s39
	s_or_b32 s48, s37, s35
	s_ashr_i32 s49, s48, 31
	s_lshl_b64 s[48:49], s[48:49], 2
	s_mov_b32 s2, 0xbfb8aa3b
	s_waitcnt lgkmcnt(0)
	s_add_u32 s38, s38, s48
	s_addc_u32 s39, s39, s49
	v_mov_b32_e32 v1, v191
	s_mov_b32 s38, 0
	s_ashr_i32 s39, s38, 31
	s_lshl_b64 s[38:39], s[38:39], 3
	s_add_u32 s38, s0, s38
	s_addc_u32 s39, s1, s39
	s_waitcnt lgkmcnt(0)
	s_add_u32 s38, s38, s48
	s_addc_u32 s39, s39, s49
	v_mov_b32_e32 v3, v192
	s_waitcnt vmcnt(0)
	v_mul_f32_e32 v0, 0xbfb8aa3b, v0
	v_exp_f32_e32 v0, v0
	v_mul_f32_e32 v1, 0x3fb8aa3b, v1
	v_exp_f32_e32 v1, v1
	v_add_f32_e32 v0, 1.0, v0
	v_rcp_f32_e32 v0, v0
	v_add_f32_e32 v2, v2, v3
	v_max_f32_e32 v4, 0, v2
	v_mul_f32_e64 v2, |v2|, s2
	v_exp_f32_e32 v5, v2
	s_mov_b32 s2, 0x3f2aaaab
	v_add_f32_e32 v6, 1.0, v5
	v_add_f32_e32 v2, -1.0, v6
	v_sub_f32_e32 v3, v2, v6
	v_add_f32_e32 v3, 1.0, v3
	v_sub_f32_e32 v2, v5, v2
	v_add_f32_e32 v7, v2, v3
	v_frexp_mant_f32_e32 v2, v6
	v_cmp_gt_f32_e32 vcc, s2, v2
	v_cvt_f64_f32_e32 v[2:3], v6
	v_frexp_exp_i32_f64_e32 v2, v[2:3]
	v_subbrev_co_u32_e32 v2, vcc, 0, v2, vcc
	v_sub_u32_e32 v3, 0, v2
	v_ldexp_f32 v6, v6, v3
	v_ldexp_f32 v3, v7, v3
	v_add_f32_e32 v7, -1.0, v6
	v_add_f32_e32 v8, 1.0, v7
	v_sub_f32_e32 v8, v6, v8
	v_add_f32_e32 v8, v3, v8
	v_add_f32_e32 v9, v7, v8
	v_sub_f32_e32 v7, v9, v7
	v_sub_f32_e32 v7, v8, v7
	v_add_f32_e32 v8, 1.0, v6
	v_add_f32_e32 v10, -1.0, v8
	v_sub_f32_e32 v6, v6, v10
	v_add_f32_e32 v3, v3, v6
	v_add_f32_e32 v6, v8, v3
	v_sub_f32_e32 v8, v6, v8
	v_sub_f32_e32 v3, v3, v8
	v_rcp_f32_e32 v8, v6
	v_cvt_f32_i32_e32 v2, v2
	s_mov_b32 s2, 0x3f317218
	v_mul_f32_e32 v10, v9, v8
	v_mul_f32_e32 v11, v6, v10
	v_fma_f32 v12, v10, v6, -v11
	v_fmac_f32_e32 v12, v10, v3
	v_add_f32_e32 v13, v11, v12
	v_sub_f32_e32 v14, v9, v13
	v_sub_f32_e32 v9, v9, v14
	v_sub_f32_e32 v11, v13, v11
	v_sub_f32_e32 v9, v9, v13
	v_add_f32_e32 v7, v7, v9
	v_sub_f32_e32 v9, v11, v12
	v_add_f32_e32 v7, v9, v7
	v_add_f32_e32 v9, v14, v7
	v_mul_f32_e32 v11, v8, v9
	v_mul_f32_e32 v12, v6, v11
	v_fma_f32 v6, v11, v6, -v12
	v_fmac_f32_e32 v6, v11, v3
	v_sub_f32_e32 v3, v14, v9
	v_add_f32_e32 v3, v7, v3
	v_add_f32_e32 v7, v12, v6
	v_sub_f32_e32 v13, v9, v7
	v_sub_f32_e32 v9, v9, v13
	v_sub_f32_e32 v12, v7, v12
	v_sub_f32_e32 v7, v9, v7
	v_add_f32_e32 v3, v3, v7
	v_sub_f32_e32 v6, v12, v6
	v_add_f32_e32 v3, v6, v3
	v_add_f32_e32 v6, v10, v11
	v_add_f32_e32 v3, v13, v3
	v_sub_f32_e32 v7, v6, v10
	v_mul_f32_e32 v3, v8, v3
	v_sub_f32_e32 v7, v11, v7
	v_add_f32_e32 v3, v7, v3
	v_mul_f32_e32 v10, 0x3f317218, v2
	v_add_f32_e32 v7, v6, v3
	v_fma_f32 v11, v2, s2, -v10
	v_mul_f32_e32 v8, v7, v7
	v_fmac_f32_e32 v11, 0xb102e308, v2
	v_sub_f32_e32 v2, v7, v6
	v_fmamk_f32 v9, v8, 0x3e9b6dac, v232
	v_sub_f32_e32 v2, v3, v2
	v_add_f32_e32 v3, v10, v11
	v_fmaak_f32 v9, v8, v9, 0x3f2aaada
	v_sub_f32_e32 v6, v3, v10
	v_ldexp_f32 v10, v7, 1
	v_mul_f32_e32 v7, v7, v8
	v_mul_f32_e32 v7, v7, v9
	v_add_f32_e32 v8, v10, v7
	v_sub_f32_e32 v9, v8, v10
	v_ldexp_f32 v2, v2, 1
	v_sub_f32_e32 v7, v7, v9
	v_add_f32_e32 v2, v2, v7
	v_add_f32_e32 v7, v8, v2
	v_sub_f32_e32 v8, v7, v8
	v_sub_f32_e32 v2, v2, v8
	v_add_f32_e32 v8, v3, v7
	v_sub_f32_e32 v9, v8, v3
	v_sub_f32_e32 v10, v8, v9
	v_sub_f32_e32 v6, v11, v6
	v_sub_f32_e32 v3, v3, v10
	v_sub_f32_e32 v7, v7, v9
	v_add_f32_e32 v3, v7, v3
	v_add_f32_e32 v7, v6, v2
	v_sub_f32_e32 v9, v7, v6
	v_sub_f32_e32 v10, v7, v9
	v_sub_f32_e32 v6, v6, v10
	v_sub_f32_e32 v2, v2, v9
	v_add_f32_e32 v3, v7, v3
	v_add_f32_e32 v2, v2, v6
	v_add_f32_e32 v6, v8, v3
	v_sub_f32_e32 v7, v6, v8
	v_sub_f32_e32 v3, v3, v7
	v_add_f32_e32 v2, v2, v3
	s_mov_b32 s2, 0x7f800000
	v_add_f32_e32 v2, v6, v2
	v_cmp_neq_f32_e32 vcc, s2, v5
	s_mov_b32 s2, 0x33800000
	s_nop 0
	v_cndmask_b32_e32 v2, v236, v2, vcc
	v_cmp_ngt_f32_e32 vcc, -1.0, v5
	s_nop 1
	v_cndmask_b32_e32 v2, v237, v2, vcc
	v_cmp_neq_f32_e32 vcc, -1.0, v5
	s_nop 1
	v_cndmask_b32_e32 v2, v238, v2, vcc
	v_cmp_lt_f32_e64 vcc, |v5|, s2
	s_nop 1
	v_cndmask_b32_e32 v2, v2, v5, vcc
	v_add_f32_e32 v2, v4, v2
	v_add_u32_e32 v4, -1, v234
	v_cmp_lt_i32_e32 vcc, v4, v111
	v_mul_f32_e64 v3, v2, -v1
	s_nop 0
	v_cndmask_b32_e32 v4, v4, v234, vcc
	v_lshlrev_b32_e32 v4, 2, v4
	ds_bpermute_b32 v4, v4, v3
	v_cmp_eq_u32_e32 vcc, 0, v106
	s_waitcnt lgkmcnt(0)
	v_fma_f32 v1, v2, -v1, v4
	v_add_u32_e32 v2, -2, v234
	v_cndmask_b32_e32 v1, v1, v3, vcc
	v_cmp_lt_i32_e32 vcc, v2, v111
	v_add_u32_e32 v3, 0x1cc00, v44
	s_nop 0
	v_cndmask_b32_e32 v2, v2, v234, vcc
	v_lshlrev_b32_e32 v2, 2, v2
	ds_bpermute_b32 v2, v2, v1
	v_cmp_gt_u32_e32 vcc, 2, v106
	s_waitcnt lgkmcnt(0)
	v_add_f32_e32 v2, v1, v2
	v_cndmask_b32_e32 v1, v2, v1, vcc
	v_add_u32_e32 v2, -4, v234
	v_cmp_lt_i32_e32 vcc, v2, v111
	s_nop 1
	v_cndmask_b32_e32 v2, v2, v234, vcc
	v_lshlrev_b32_e32 v2, 2, v2
	ds_bpermute_b32 v2, v2, v1
	v_cmp_gt_u32_e32 vcc, 4, v106
	s_waitcnt lgkmcnt(0)
	v_add_f32_e32 v2, v1, v2
	v_cndmask_b32_e32 v1, v2, v1, vcc
	v_add_u32_e32 v2, -8, v234
	v_cmp_lt_i32_e32 vcc, v2, v111
	s_nop 1
	v_cndmask_b32_e32 v2, v2, v234, vcc
	v_lshlrev_b32_e32 v2, 2, v2
	ds_bpermute_b32 v2, v2, v1
	v_cmp_gt_u32_e32 vcc, 8, v106
	s_waitcnt lgkmcnt(0)
	v_add_f32_e32 v2, v1, v2
	v_cndmask_b32_e32 v1, v2, v1, vcc
	v_add_u32_e32 v2, -16, v234
	v_cmp_lt_i32_e32 vcc, v2, v111
	s_nop 1
	v_cndmask_b32_e32 v2, v2, v234, vcc
	v_lshlrev_b32_e32 v2, 2, v2
	ds_bpermute_b32 v2, v2, v1
	v_cmp_gt_u32_e32 vcc, 16, v106
	s_waitcnt lgkmcnt(0)
	v_add_f32_e32 v2, v1, v2
	v_cndmask_b32_e32 v2, v2, v1, vcc
	v_subrev_u32_e32 v1, 32, v234
	v_cmp_lt_i32_e32 vcc, v1, v111
	s_nop 1
	v_cndmask_b32_e32 v1, v1, v234, vcc
	v_lshlrev_b32_e32 v1, 2, v1
	ds_bpermute_b32 v1, v1, v2
	v_cmp_gt_u32_e32 vcc, 32, v106
	s_waitcnt lgkmcnt(0)
	v_add_f32_e32 v1, v2, v1
	v_cndmask_b32_e32 v2, v1, v2, vcc
	ds_write_b32 v3, v2
	v_add_u32_e32 v2, 0x1cd00, v44
	v_cmp_eq_u32_e32 vcc, 63, v106
	ds_write_b32 v2, v0
	s_and_b64 exec, exec, vcc
	s_cbranch_execz .LBB0_763
	v_mul_f32_e32 v0, 0x3fb8aa3b, v1
	v_exp_f32_e32 v2, v0
	v_mov_b64_e32 v[0:1], s[92:93]
	global_store_dword v[0:1], v2, off
